# K-loops of all four GEMMs: LDS-DMA loads switched to scalar-base addressing (global_load_lds vOFF, s[base]); the 16 per-iteration v_lshl_add_u64 become SALU adds
# speedup vs baseline: 1.0161x; 1.0071x over previous
; #define PG8_STAGE(bufoff, gbase, voff) do { _Pragma("unroll") for (int _i = 0; _i < 2; ++_i) \
;         __builtin_amdgcn_global_load_lds((const unsigned*)((const char*)(gbase) + (voff)[_i]), (PG8_LAS unsigned*)(lds + (bufoff) + ldsw + _i * 8192), 16, 0, 0); } while (0)
; #define PG8_LDA(dst, b, h) do { _Pragma("unroll") for (int m = 0; m < 4; ++m) _Pragma("unroll") for (int k = 0; k < 2; ++k) dst[m][k] = *(const PG8_LAS bf16x8*)(lds + PG8_SA(b, h) + aoff + m * 2048 + k * 1024); } while (0)
; #define PG8_LDB(dst, b, h) do { _Pragma("unroll") for (int n = 0; n < 2; ++n) _Pragma("unroll") for (int k = 0; k < 2; ++k) dst[n][k] = *(const PG8_LAS bf16x8*)(lds + PG8_SB(b, h) + boff + n * 2048 + k * 1024); } while (0)
; #define PG8_MMA(ai, bj, At, Bt) do { __builtin_amdgcn_s_setprio(1); _Pragma("unroll") for (int m = 0; m < 4; ++m) _Pragma("unroll") for (int n = 0; n < 2; ++n) _Pragma("unroll") for (int k = 0; k < 2; ++k) \
;         acc[ai][bj][m][n] = __builtin_amdgcn_mfma_f32_16x16x32_bf16(Bt[n][k], At[m][k], acc[ai][bj][m][n], 0, 0, 0); __builtin_amdgcn_s_setprio(0); } while (0)
; #define PG8_WAIT_V(n) asm volatile("s_waitcnt vmcnt(" #n ")" ::: "memory")
; #define PG8_WAIT_L(n) asm volatile("s_waitcnt lgkmcnt(" #n ")" ::: "memory")
; #define PG8_BAR __builtin_amdgcn_s_barrier()
; #define PG8_SCHED __builtin_amdgcn_sched_barrier(0)
; template <class Epi, class Sched, bool ALIGN_EPI = false, bool SP2 = false>
; __device__ __forceinline__ void gemm_phase(PG8_LAS unsigned char* lds, const Gemm g, const Sched& S, const Epi& E) {
;     ...
;             if constexpr (SP2) {
;             PG8_LDB(B0, 0, 0); PG8_LDB(B1, 0, 1); PG8_SCHED; PG8_LDA(At, 0, 0); PG8_STAGE(PG8_SA(1, 1), a1 + hstep, voffA);
;             PG8_WAIT_V(8); PG8_WAIT_L(0); PG8_BAR; PG8_MMA(0, 0, At, B0); PG8_MMA(0, 1, At, B1); PG8_BAR; PG8_SCHED;
;             PG8_LDA(At, 0, 1); PG8_STAGE(PG8_SB(0, 0), b2, voffB); PG8_STAGE(PG8_SB(0, 1), b2 + hstep, voffB); PG8_STAGE(PG8_SA(0, 0), a2, voffA);
;             PG8_WAIT_V(8); PG8_WAIT_L(0); PG8_BAR; PG8_MMA(1, 0, At, B0); PG8_MMA(1, 1, At, B1); PG8_BAR; PG8_SCHED;
.LBB0_68:
	ds_read_b128 v[128:131], v203
	ds_read_b128 v[132:135], v203 offset:1024
	ds_read_b128 v[136:139], v203 offset:2048
	ds_read_b128 v[140:143], v203 offset:3072
	ds_read_b128 v[144:147], v204
	ds_read_b128 v[148:151], v204 offset:1024
	ds_read_b128 v[180:183], v204 offset:2048
	ds_read_b128 v[184:187], v204 offset:3072
	s_add_u32 s30, s82, 0xfff80080
	s_addc_u32 s31, s83, -1
	s_cmp_eq_u32 s29, 28
	s_cselect_b32 s87, s1, s31
	s_cselect_b32 s86, s75, s30
	s_cselect_b32 s85, s73, vcc_hi
	s_cselect_b32 s84, s81, vcc_lo
	s_add_i32 m0, s94, 0xc000
	ds_read_b128 v[206:209], v205
	ds_read_b128 v[210:213], v205 offset:1024
	ds_read_b128 v[214:217], v205 offset:2048
	ds_read_b128 v[218:221], v205 offset:3072
	ds_read_b128 v[222:225], v205 offset:4096
	ds_read_b128 v[226:229], v205 offset:5120
	ds_read_b128 v[230:233], v205 offset:6144
	ds_read_b128 v[234:237], v205 offset:7168
	global_load_lds_dwordx4 v170, s[82:83]
	s_add_i32 m0, s94, 0xe000
	s_nop 0
	global_load_lds_dwordx4 v172, s[82:83]
	s_waitcnt vmcnt(8)
	s_waitcnt lgkmcnt(0)
	s_barrier
	s_setprio 1
	s_waitcnt lgkmcnt(0)
	v_mfma_f32_16x16x32_bf16 v[124:127], v[128:131], v[206:209], v[124:127]
	v_mfma_f32_16x16x32_bf16 v[120:123], v[136:139], v[206:209], v[120:123]
	v_mfma_f32_16x16x32_bf16 v[116:119], v[128:131], v[214:217], v[116:119]
	v_mfma_f32_16x16x32_bf16 v[112:115], v[136:139], v[214:217], v[112:115]
	v_mfma_f32_16x16x32_bf16 v[108:111], v[128:131], v[222:225], v[108:111]
	v_mfma_f32_16x16x32_bf16 v[104:107], v[136:139], v[222:225], v[104:107]
	v_mfma_f32_16x16x32_bf16 v[100:103], v[128:131], v[230:233], v[100:103]
	v_mfma_f32_16x16x32_bf16 v[96:99], v[136:139], v[230:233], v[96:99]
	v_mfma_f32_16x16x32_bf16 v[124:127], v[132:135], v[210:213], v[124:127]
	v_mfma_f32_16x16x32_bf16 v[120:123], v[140:143], v[210:213], v[120:123]
	v_mfma_f32_16x16x32_bf16 v[116:119], v[132:135], v[218:221], v[116:119]
	v_mfma_f32_16x16x32_bf16 v[112:115], v[140:143], v[218:221], v[112:115]
	v_mfma_f32_16x16x32_bf16 v[108:111], v[132:135], v[226:229], v[108:111]
	v_mfma_f32_16x16x32_bf16 v[104:107], v[140:143], v[226:229], v[104:107]
	v_mfma_f32_16x16x32_bf16 v[100:103], v[132:135], v[234:237], v[100:103]
	v_mfma_f32_16x16x32_bf16 v[96:99], v[140:143], v[234:237], v[96:99]
	s_setprio 0
	s_setprio 1
	v_mfma_f32_16x16x32_bf16 v[68:71], v[144:147], v[206:209], v[68:71]
	v_mfma_f32_16x16x32_bf16 v[64:67], v[180:183], v[206:209], v[64:67]
	v_mfma_f32_16x16x32_bf16 v[52:55], v[144:147], v[214:217], v[52:55]
	v_mfma_f32_16x16x32_bf16 v[48:51], v[180:183], v[214:217], v[48:51]
	v_mfma_f32_16x16x32_bf16 v[44:47], v[144:147], v[222:225], v[44:47]
	v_mfma_f32_16x16x32_bf16 v[40:43], v[180:183], v[222:225], v[40:43]
	v_mfma_f32_16x16x32_bf16 v[36:39], v[144:147], v[230:233], v[36:39]
	v_mfma_f32_16x16x32_bf16 v[32:35], v[180:183], v[230:233], v[32:35]
	v_mfma_f32_16x16x32_bf16 v[68:71], v[148:151], v[210:213], v[68:71]
	v_mfma_f32_16x16x32_bf16 v[64:67], v[184:187], v[210:213], v[64:67]
	v_mfma_f32_16x16x32_bf16 v[52:55], v[148:151], v[218:221], v[52:55]
	v_mfma_f32_16x16x32_bf16 v[48:51], v[184:187], v[218:221], v[48:51]
	v_mfma_f32_16x16x32_bf16 v[44:47], v[148:151], v[226:229], v[44:47]
	v_mfma_f32_16x16x32_bf16 v[40:43], v[184:187], v[226:229], v[40:43]
	v_mfma_f32_16x16x32_bf16 v[36:39], v[148:151], v[234:237], v[36:39]
	v_mfma_f32_16x16x32_bf16 v[32:35], v[184:187], v[234:237], v[32:35]
	s_setprio 0
	s_barrier
	s_add_i32 s30, s47, s92
	s_mov_b32 m0, s30
	ds_read_b128 v[206:209], v205 offset:16384
	ds_read_b128 v[210:213], v205 offset:17408
	ds_read_b128 v[214:217], v205 offset:18432
	ds_read_b128 v[218:221], v205 offset:19456
	ds_read_b128 v[222:225], v205 offset:20480
	ds_read_b128 v[226:229], v205 offset:21504
	ds_read_b128 v[230:233], v205 offset:22528
	ds_read_b128 v[234:237], v205 offset:23552
	global_load_lds_dwordx4 v158, s[84:85]
	s_add_i32 m0, s30, 0x2000
	s_add_u32 s30, s84, 0x80000
	s_addc_u32 s31, s85, 0
	s_add_i32 s89, s33, s92
	global_load_lds_dwordx4 v154, s[84:85]
	s_mov_b32 m0, s89
	s_nop 0
	global_load_lds_dwordx4 v158, s[30:31]
	s_add_i32 m0, s89, 0x2000
	s_nop 0
	global_load_lds_dwordx4 v154, s[30:31]
	s_mov_b32 m0, s94
	s_nop 0
	global_load_lds_dwordx4 v160, s[86:87]
	s_mov_b32 m0, s95
	s_nop 0
	global_load_lds_dwordx4 v156, s[86:87]
	s_waitcnt vmcnt(8)
	s_waitcnt lgkmcnt(0)
	s_barrier
	s_setprio 1
	s_waitcnt lgkmcnt(0)
	v_mfma_f32_16x16x32_bf16 v[92:95], v[128:131], v[206:209], v[92:95]
	v_mfma_f32_16x16x32_bf16 v[88:91], v[136:139], v[206:209], v[88:91]
	v_mfma_f32_16x16x32_bf16 v[84:87], v[128:131], v[214:217], v[84:87]
	v_mfma_f32_16x16x32_bf16 v[80:83], v[136:139], v[214:217], v[80:83]
	v_mfma_f32_16x16x32_bf16 v[76:79], v[128:131], v[222:225], v[76:79]
	v_mfma_f32_16x16x32_bf16 v[72:75], v[136:139], v[222:225], v[72:75]
	v_mfma_f32_16x16x32_bf16 v[60:63], v[128:131], v[230:233], v[60:63]
	v_mfma_f32_16x16x32_bf16 v[56:59], v[136:139], v[230:233], v[56:59]
	v_mfma_f32_16x16x32_bf16 v[92:95], v[132:135], v[210:213], v[92:95]
	v_mfma_f32_16x16x32_bf16 v[88:91], v[140:143], v[210:213], v[88:91]
	v_mfma_f32_16x16x32_bf16 v[84:87], v[132:135], v[218:221], v[84:87]
	v_mfma_f32_16x16x32_bf16 v[80:83], v[140:143], v[218:221], v[80:83]
	v_mfma_f32_16x16x32_bf16 v[76:79], v[132:135], v[226:229], v[76:79]
	v_mfma_f32_16x16x32_bf16 v[72:75], v[140:143], v[226:229], v[72:75]
	v_mfma_f32_16x16x32_bf16 v[60:63], v[132:135], v[234:237], v[60:63]
	v_mfma_f32_16x16x32_bf16 v[56:59], v[140:143], v[234:237], v[56:59]
	s_setprio 0
	s_setprio 1
	v_mfma_f32_16x16x32_bf16 v[28:31], v[144:147], v[206:209], v[28:31]
	v_mfma_f32_16x16x32_bf16 v[24:27], v[180:183], v[206:209], v[24:27]
	v_mfma_f32_16x16x32_bf16 v[20:23], v[144:147], v[214:217], v[20:23]
	v_mfma_f32_16x16x32_bf16 v[16:19], v[180:183], v[214:217], v[16:19]
	v_mfma_f32_16x16x32_bf16 v[12:15], v[144:147], v[222:225], v[12:15]
	v_mfma_f32_16x16x32_bf16 v[8:11], v[180:183], v[222:225], v[8:11]
	v_mfma_f32_16x16x32_bf16 v[4:7], v[144:147], v[230:233], v[4:7]
	v_mfma_f32_16x16x32_bf16 v[0:3], v[180:183], v[230:233], v[0:3]
	v_mfma_f32_16x16x32_bf16 v[28:31], v[148:151], v[210:213], v[28:31]
	v_mfma_f32_16x16x32_bf16 v[24:27], v[184:187], v[210:213], v[24:27]
	v_mfma_f32_16x16x32_bf16 v[20:23], v[148:151], v[218:221], v[20:23]
	v_mfma_f32_16x16x32_bf16 v[16:19], v[184:187], v[218:221], v[16:19]
	v_mfma_f32_16x16x32_bf16 v[12:15], v[148:151], v[226:229], v[12:15]
	v_mfma_f32_16x16x32_bf16 v[8:11], v[184:187], v[226:229], v[8:11]
	v_mfma_f32_16x16x32_bf16 v[4:7], v[148:151], v[234:237], v[4:7]
	v_mfma_f32_16x16x32_bf16 v[0:3], v[184:187], v[234:237], v[0:3]
	s_setprio 0
	s_barrier
; #define PG8_STAGE(bufoff, gbase, voff) do { _Pragma("unroll") for (int _i = 0; _i < 2; ++_i) \
;         __builtin_amdgcn_global_load_lds((const unsigned*)((const char*)(gbase) + (voff)[_i]), (PG8_LAS unsigned*)(lds + (bufoff) + ldsw + _i * 8192), 16, 0, 0); } while (0)
; #define PG8_LDA(dst, b, h) do { _Pragma("unroll") for (int m = 0; m < 4; ++m) _Pragma("unroll") for (int k = 0; k < 2; ++k) dst[m][k] = *(const PG8_LAS bf16x8*)(lds + PG8_SA(b, h) + aoff + m * 2048 + k * 1024); } while (0)
; #define PG8_LDB(dst, b, h) do { _Pragma("unroll") for (int n = 0; n < 2; ++n) _Pragma("unroll") for (int k = 0; k < 2; ++k) dst[n][k] = *(const PG8_LAS bf16x8*)(lds + PG8_SB(b, h) + boff + n * 2048 + k * 1024); } while (0)
; #define PG8_MMA(ai, bj, At, Bt) do { __builtin_amdgcn_s_setprio(1); _Pragma("unroll") for (int m = 0; m < 4; ++m) _Pragma("unroll") for (int n = 0; n < 2; ++n) _Pragma("unroll") for (int k = 0; k < 2; ++k) \
;         acc[ai][bj][m][n] = __builtin_amdgcn_mfma_f32_16x16x32_bf16(Bt[n][k], At[m][k], acc[ai][bj][m][n], 0, 0, 0); __builtin_amdgcn_s_setprio(0); } while (0)
; #define PG8_WAIT_V(n) asm volatile("s_waitcnt vmcnt(" #n ")" ::: "memory")
; #define PG8_WAIT_L(n) asm volatile("s_waitcnt lgkmcnt(" #n ")" ::: "memory")
; #define PG8_BAR __builtin_amdgcn_s_barrier()
; #define PG8_SCHED __builtin_amdgcn_sched_barrier(0)
; template <class Epi, class Sched, bool ALIGN_EPI = false, bool SP2 = false>
; __device__ __forceinline__ void gemm_phase(PG8_LAS unsigned char* lds, const Gemm g, const Sched& S, const Epi& E) {
;     ...
;             PG8_LDB(B0, 1, 0); PG8_LDB(B1, 1, 1); PG8_SCHED; PG8_LDA(At, 1, 0); PG8_STAGE(PG8_SA(0, 1), a2 + hstep, voffA);
;             PG8_WAIT_V(8); PG8_WAIT_L(0); PG8_BAR; PG8_MMA(0, 0, At, B0); PG8_MMA(0, 1, At, B1); PG8_BAR; PG8_SCHED;
;             PG8_LDA(At, 1, 1); PG8_STAGE(PG8_SB(1, 0), b3, voffB); PG8_STAGE(PG8_SB(1, 1), b3 + hstep, voffB); PG8_STAGE(PG8_SA(1, 0), a3, voffA);
;             PG8_WAIT_V(8); PG8_WAIT_L(0); PG8_BAR; PG8_MMA(1, 0, At, B0); PG8_MMA(1, 1, At, B1); PG8_BAR; PG8_SCHED;
;     ...
;         if constexpr (ALIGN_EPI) { if (wr == 0) PG8_BAR; }
	s_add_i32 s89, 0, 0x18000
	s_add_i32 s54, 0, 0x1c000
	v_add_u32_e32 v140, s89, v190
	v_add_u32_e32 v162, s54, v190
	ds_read_b128 v[128:131], v140
	ds_read_b128 v[132:135], v140 offset:1024
	ds_read_b128 v[136:139], v140 offset:2048
	ds_read_b128 v[140:143], v140 offset:3072
	ds_read_b128 v[144:147], v162
	ds_read_b128 v[148:151], v162 offset:1024
	ds_read_b128 v[180:183], v162 offset:2048
	ds_read_b128 v[184:187], v162 offset:3072
	s_add_u32 s30, s86, 0x80000
	s_addc_u32 s31, s87, 0
	s_mov_b32 m0, s96
	ds_read_b128 v[206:209], v205 offset:32768
	ds_read_b128 v[210:213], v205 offset:33792
	ds_read_b128 v[214:217], v205 offset:34816
	ds_read_b128 v[218:221], v205 offset:35840
	ds_read_b128 v[222:225], v205 offset:36864
	ds_read_b128 v[226:229], v205 offset:37888
	ds_read_b128 v[230:233], v205 offset:38912
	ds_read_b128 v[234:237], v205 offset:39936
	global_load_lds_dwordx4 v160, s[30:31]
	s_mov_b32 m0, s97
	s_nop 0
	global_load_lds_dwordx4 v156, s[30:31]
	s_waitcnt vmcnt(8)
	s_waitcnt lgkmcnt(0)
	s_barrier
	s_setprio 1
	s_waitcnt lgkmcnt(0)
	v_mfma_f32_16x16x32_bf16 v[124:127], v[128:131], v[206:209], v[124:127]
	v_mfma_f32_16x16x32_bf16 v[120:123], v[136:139], v[206:209], v[120:123]
	v_mfma_f32_16x16x32_bf16 v[116:119], v[128:131], v[214:217], v[116:119]
	v_mfma_f32_16x16x32_bf16 v[112:115], v[136:139], v[214:217], v[112:115]
	v_mfma_f32_16x16x32_bf16 v[108:111], v[128:131], v[222:225], v[108:111]
	v_mfma_f32_16x16x32_bf16 v[104:107], v[136:139], v[222:225], v[104:107]
	v_mfma_f32_16x16x32_bf16 v[100:103], v[128:131], v[230:233], v[100:103]
	v_mfma_f32_16x16x32_bf16 v[96:99], v[136:139], v[230:233], v[96:99]
	v_mfma_f32_16x16x32_bf16 v[124:127], v[132:135], v[210:213], v[124:127]
	v_mfma_f32_16x16x32_bf16 v[120:123], v[140:143], v[210:213], v[120:123]
	v_mfma_f32_16x16x32_bf16 v[116:119], v[132:135], v[218:221], v[116:119]
	v_mfma_f32_16x16x32_bf16 v[112:115], v[140:143], v[218:221], v[112:115]
	v_mfma_f32_16x16x32_bf16 v[108:111], v[132:135], v[226:229], v[108:111]
	v_mfma_f32_16x16x32_bf16 v[104:107], v[140:143], v[226:229], v[104:107]
	v_mfma_f32_16x16x32_bf16 v[100:103], v[132:135], v[234:237], v[100:103]
	v_mfma_f32_16x16x32_bf16 v[96:99], v[140:143], v[234:237], v[96:99]
	s_setprio 0
	s_setprio 1
	v_mfma_f32_16x16x32_bf16 v[68:71], v[144:147], v[206:209], v[68:71]
	v_mfma_f32_16x16x32_bf16 v[64:67], v[180:183], v[206:209], v[64:67]
	v_mfma_f32_16x16x32_bf16 v[52:55], v[144:147], v[214:217], v[52:55]
	v_mfma_f32_16x16x32_bf16 v[48:51], v[180:183], v[214:217], v[48:51]
	v_mfma_f32_16x16x32_bf16 v[44:47], v[144:147], v[222:225], v[44:47]
	v_mfma_f32_16x16x32_bf16 v[40:43], v[180:183], v[222:225], v[40:43]
	v_mfma_f32_16x16x32_bf16 v[36:39], v[144:147], v[230:233], v[36:39]
	v_mfma_f32_16x16x32_bf16 v[32:35], v[180:183], v[230:233], v[32:35]
	v_mfma_f32_16x16x32_bf16 v[68:71], v[148:151], v[210:213], v[68:71]
	v_mfma_f32_16x16x32_bf16 v[64:67], v[184:187], v[210:213], v[64:67]
	v_mfma_f32_16x16x32_bf16 v[52:55], v[148:151], v[218:221], v[52:55]
	v_mfma_f32_16x16x32_bf16 v[48:51], v[184:187], v[218:221], v[48:51]
	v_mfma_f32_16x16x32_bf16 v[44:47], v[148:151], v[226:229], v[44:47]
	v_mfma_f32_16x16x32_bf16 v[40:43], v[184:187], v[226:229], v[40:43]
	v_mfma_f32_16x16x32_bf16 v[36:39], v[148:151], v[234:237], v[36:39]
	v_mfma_f32_16x16x32_bf16 v[32:35], v[184:187], v[234:237], v[32:35]
	s_setprio 0
	s_barrier
	s_add_i32 s30, s89, s92
	s_mov_b32 m0, s30
	ds_read_b128 v[206:209], v205 offset:49152
	ds_read_b128 v[210:213], v205 offset:50176
	ds_read_b128 v[214:217], v205 offset:51200
	ds_read_b128 v[218:221], v205 offset:52224
	ds_read_b128 v[222:225], v205 offset:53248
	ds_read_b128 v[226:229], v205 offset:54272
	ds_read_b128 v[230:233], v205 offset:55296
	ds_read_b128 v[234:237], v205 offset:56320
	s_add_u32 s62, s84, 0x80
	s_addc_u32 s63, s85, 0
	global_load_lds_dwordx4 v158, s[62:63]
	s_add_i32 m0, s30, 0x2000
	s_add_u32 s30, s84, 0x80080
	s_addc_u32 s31, s85, 0
	s_add_i32 s54, s54, s92
	global_load_lds_dwordx4 v154, s[62:63]
	s_mov_b32 m0, s54
	s_nop 0
	global_load_lds_dwordx4 v158, s[30:31]
	s_add_i32 m0, s54, 0x2000
	s_nop 0
	global_load_lds_dwordx4 v154, s[30:31]
	s_mov_b32 m0, s88
	s_nop 0
	s_add_u32 s62, s86, 0x80
	s_addc_u32 s63, s87, 0
	global_load_lds_dwordx4 v160, s[62:63]
	s_mov_b32 m0, s46
	s_nop 0
	global_load_lds_dwordx4 v156, s[62:63]
	s_waitcnt vmcnt(8)
	s_waitcnt lgkmcnt(0)
	s_barrier
	s_setprio 1
	s_waitcnt lgkmcnt(0)
	v_mfma_f32_16x16x32_bf16 v[92:95], v[128:131], v[206:209], v[92:95]
	v_mfma_f32_16x16x32_bf16 v[88:91], v[136:139], v[206:209], v[88:91]
	v_mfma_f32_16x16x32_bf16 v[84:87], v[128:131], v[214:217], v[84:87]
	v_mfma_f32_16x16x32_bf16 v[80:83], v[136:139], v[214:217], v[80:83]
	v_mfma_f32_16x16x32_bf16 v[76:79], v[128:131], v[222:225], v[76:79]
	v_mfma_f32_16x16x32_bf16 v[72:75], v[136:139], v[222:225], v[72:75]
	v_mfma_f32_16x16x32_bf16 v[60:63], v[128:131], v[230:233], v[60:63]
	v_mfma_f32_16x16x32_bf16 v[56:59], v[136:139], v[230:233], v[56:59]
	v_mfma_f32_16x16x32_bf16 v[92:95], v[132:135], v[210:213], v[92:95]
	v_mfma_f32_16x16x32_bf16 v[88:91], v[140:143], v[210:213], v[88:91]
	v_mfma_f32_16x16x32_bf16 v[84:87], v[132:135], v[218:221], v[84:87]
	v_mfma_f32_16x16x32_bf16 v[80:83], v[140:143], v[218:221], v[80:83]
	v_mfma_f32_16x16x32_bf16 v[76:79], v[132:135], v[226:229], v[76:79]
	v_mfma_f32_16x16x32_bf16 v[72:75], v[140:143], v[226:229], v[72:75]
	v_mfma_f32_16x16x32_bf16 v[60:63], v[132:135], v[234:237], v[60:63]
	v_mfma_f32_16x16x32_bf16 v[56:59], v[140:143], v[234:237], v[56:59]
	s_setprio 0
	s_setprio 1
	v_mfma_f32_16x16x32_bf16 v[28:31], v[144:147], v[206:209], v[28:31]
	v_mfma_f32_16x16x32_bf16 v[24:27], v[180:183], v[206:209], v[24:27]
	v_mfma_f32_16x16x32_bf16 v[20:23], v[144:147], v[214:217], v[20:23]
	v_mfma_f32_16x16x32_bf16 v[16:19], v[180:183], v[214:217], v[16:19]
	v_mfma_f32_16x16x32_bf16 v[12:15], v[144:147], v[222:225], v[12:15]
	v_mfma_f32_16x16x32_bf16 v[8:11], v[180:183], v[222:225], v[8:11]
	v_mfma_f32_16x16x32_bf16 v[4:7], v[144:147], v[230:233], v[4:7]
	v_mfma_f32_16x16x32_bf16 v[0:3], v[180:183], v[230:233], v[0:3]
	v_mfma_f32_16x16x32_bf16 v[28:31], v[148:151], v[210:213], v[28:31]
	v_mfma_f32_16x16x32_bf16 v[24:27], v[184:187], v[210:213], v[24:27]
	v_mfma_f32_16x16x32_bf16 v[20:23], v[148:151], v[218:221], v[20:23]
	v_mfma_f32_16x16x32_bf16 v[16:19], v[184:187], v[218:221], v[16:19]
	v_mfma_f32_16x16x32_bf16 v[12:15], v[148:151], v[226:229], v[12:15]
	v_mfma_f32_16x16x32_bf16 v[8:11], v[184:187], v[226:229], v[8:11]
	v_mfma_f32_16x16x32_bf16 v[4:7], v[148:151], v[234:237], v[4:7]
	v_mfma_f32_16x16x32_bf16 v[0:3], v[184:187], v[234:237], v[0:3]
	s_setprio 0
	s_barrier
	s_add_i32 s29, s29, 2
	s_add_u32 s82, s82, 0x100
	s_addc_u32 s83, s83, 0
	s_add_u32 vcc_lo, vcc_lo, 0x100
	s_addc_u32 vcc_hi, vcc_hi, 0
	s_cmp_gt_u32 s29, 29
	s_cbranch_scc0 .LBB0_68
	s_and_b64 vcc, exec, s[64:65]
	s_cbranch_vccz .LBB0_71
	s_barrier

; #define PG8_STAGE(bufoff, gbase, voff) do { _Pragma("unroll") for (int _i = 0; _i < 2; ++_i) \
;         __builtin_amdgcn_global_load_lds((const unsigned*)((const char*)(gbase) + (voff)[_i]), (PG8_LAS unsigned*)(lds + (bufoff) + ldsw + _i * 8192), 16, 0, 0); } while (0)
; #define PG8_LDA(dst, b, h) do { _Pragma("unroll") for (int m = 0; m < 4; ++m) _Pragma("unroll") for (int k = 0; k < 2; ++k) dst[m][k] = *(const PG8_LAS bf16x8*)(lds + PG8_SA(b, h) + aoff + m * 2048 + k * 1024); } while (0)
; #define PG8_LDB(dst, b, h) do { _Pragma("unroll") for (int n = 0; n < 2; ++n) _Pragma("unroll") for (int k = 0; k < 2; ++k) dst[n][k] = *(const PG8_LAS bf16x8*)(lds + PG8_SB(b, h) + boff + n * 2048 + k * 1024); } while (0)
; #define PG8_MMA(ai, bj, At, Bt) do { __builtin_amdgcn_s_setprio(1); _Pragma("unroll") for (int m = 0; m < 4; ++m) _Pragma("unroll") for (int n = 0; n < 2; ++n) _Pragma("unroll") for (int k = 0; k < 2; ++k) \
;         acc[ai][bj][m][n] = __builtin_amdgcn_mfma_f32_16x16x32_bf16(Bt[n][k], At[m][k], acc[ai][bj][m][n], 0, 0, 0); __builtin_amdgcn_s_setprio(0); } while (0)
; #define PG8_WAIT_V(n) asm volatile("s_waitcnt vmcnt(" #n ")" ::: "memory")
; #define PG8_WAIT_L(n) asm volatile("s_waitcnt lgkmcnt(" #n ")" ::: "memory")
; template <class Epi, class Sched, bool ALIGN_EPI = false, bool SP2 = false>
; __device__ __forceinline__ void gemm_phase(PG8_LAS unsigned char* lds, const Gemm g, const Sched& S, const Epi& E) {
;     ...
;             const bool last = (t == nt - 2);
;             const char* a1 = cA + (size_t)(t + 1) * kstep;
;             const char* a2 = last ? nA : cA + (size_t)(t + 2) * kstep; const char* b2 = last ? nB : cB + (size_t)(t + 2) * kstep;
;             const char* a3 = a2 + kstep; const char* b3 = b2 + kstep;
;             if (last && has_next) S.a_ready(nxt);
;             if constexpr (SP2) {
;             PG8_LDB(B0, 0, 0); PG8_LDB(B1, 0, 1); PG8_SCHED; PG8_LDA(At, 0, 0); PG8_STAGE(PG8_SA(1, 1), a1 + hstep, voffA);
;             PG8_WAIT_V(8); PG8_WAIT_L(0); PG8_BAR; PG8_MMA(0, 0, At, B0); PG8_MMA(0, 1, At, B1); PG8_BAR; PG8_SCHED;
;             PG8_LDA(At, 0, 1); PG8_STAGE(PG8_SB(0, 0), b2, voffB); PG8_STAGE(PG8_SB(0, 1), b2 + hstep, voffB); PG8_STAGE(PG8_SA(0, 0), a2, voffA);
;             PG8_WAIT_V(8); PG8_WAIT_L(0); PG8_BAR; PG8_MMA(1, 0, At, B0); PG8_MMA(1, 1, At, B1); PG8_BAR; PG8_SCHED;
.LBB0_283:
	ds_read_b128 v[152:155], v149
	ds_read_b128 v[156:159], v149 offset:1024
	ds_read_b128 v[160:163], v149 offset:2048
	ds_read_b128 v[164:167], v149 offset:3072
	ds_read_b128 v[168:171], v150
	ds_read_b128 v[172:175], v150 offset:1024
	ds_read_b128 v[180:183], v150 offset:2048
	ds_read_b128 v[184:187], v150 offset:3072
	s_add_u32 s30, s66, 0xfff80080
	s_addc_u32 s31, s67, -1
	s_cmp_eq_u32 s85, 28
	s_cselect_b32 s71, s59, s31
	s_cselect_b32 s70, s81, s30
	s_cselect_b32 s69, s57, s84
	s_cselect_b32 s68, s82, s83
	s_add_i32 m0, s29, 0xc000
	ds_read_b128 v[188:191], v151
	ds_read_b128 v[192:195], v151 offset:1024
	ds_read_b128 v[196:199], v151 offset:2048
	ds_read_b128 v[200:203], v151 offset:3072
	ds_read_b128 v[204:207], v151 offset:4096
	ds_read_b128 v[208:211], v151 offset:5120
	ds_read_b128 v[212:215], v151 offset:6144
	ds_read_b128 v[216:219], v151 offset:7168
	global_load_lds_dwordx4 v136, s[66:67]
	s_add_i32 m0, s29, 0xe000
	s_nop 0
	global_load_lds_dwordx4 v138, s[66:67]
	s_waitcnt vmcnt(8)
	s_waitcnt lgkmcnt(0)
	s_barrier
	s_setprio 1
	s_waitcnt lgkmcnt(0)
	v_mfma_f32_16x16x32_bf16 v[124:127], v[152:155], v[188:191], v[124:127]
	v_mfma_f32_16x16x32_bf16 v[120:123], v[160:163], v[188:191], v[120:123]
	v_mfma_f32_16x16x32_bf16 v[116:119], v[152:155], v[196:199], v[116:119]
	v_mfma_f32_16x16x32_bf16 v[108:111], v[160:163], v[196:199], v[108:111]
	v_mfma_f32_16x16x32_bf16 v[100:103], v[152:155], v[204:207], v[100:103]
	v_mfma_f32_16x16x32_bf16 v[92:95], v[160:163], v[204:207], v[92:95]
	v_mfma_f32_16x16x32_bf16 v[84:87], v[152:155], v[212:215], v[84:87]
	v_mfma_f32_16x16x32_bf16 v[76:79], v[160:163], v[212:215], v[76:79]
	v_mfma_f32_16x16x32_bf16 v[124:127], v[156:159], v[192:195], v[124:127]
	v_mfma_f32_16x16x32_bf16 v[120:123], v[164:167], v[192:195], v[120:123]
	v_mfma_f32_16x16x32_bf16 v[116:119], v[156:159], v[200:203], v[116:119]
	v_mfma_f32_16x16x32_bf16 v[108:111], v[164:167], v[200:203], v[108:111]
	v_mfma_f32_16x16x32_bf16 v[100:103], v[156:159], v[208:211], v[100:103]
	v_mfma_f32_16x16x32_bf16 v[92:95], v[164:167], v[208:211], v[92:95]
	v_mfma_f32_16x16x32_bf16 v[84:87], v[156:159], v[216:219], v[84:87]
	v_mfma_f32_16x16x32_bf16 v[76:79], v[164:167], v[216:219], v[76:79]
	s_setprio 0
	s_setprio 1
	v_mfma_f32_16x16x32_bf16 v[112:115], v[168:171], v[188:191], v[112:115]
	v_mfma_f32_16x16x32_bf16 v[104:107], v[180:183], v[188:191], v[104:107]
	v_mfma_f32_16x16x32_bf16 v[96:99], v[168:171], v[196:199], v[96:99]
	v_mfma_f32_16x16x32_bf16 v[88:91], v[180:183], v[196:199], v[88:91]
	v_mfma_f32_16x16x32_bf16 v[80:83], v[168:171], v[204:207], v[80:83]
	v_mfma_f32_16x16x32_bf16 v[72:75], v[180:183], v[204:207], v[72:75]
	v_mfma_f32_16x16x32_bf16 v[68:71], v[168:171], v[212:215], v[68:71]
	v_mfma_f32_16x16x32_bf16 v[64:67], v[180:183], v[212:215], v[64:67]
	v_mfma_f32_16x16x32_bf16 v[112:115], v[172:175], v[192:195], v[112:115]
	v_mfma_f32_16x16x32_bf16 v[104:107], v[184:187], v[192:195], v[104:107]
	v_mfma_f32_16x16x32_bf16 v[96:99], v[172:175], v[200:203], v[96:99]
	v_mfma_f32_16x16x32_bf16 v[88:91], v[184:187], v[200:203], v[88:91]
	v_mfma_f32_16x16x32_bf16 v[80:83], v[172:175], v[208:211], v[80:83]
	v_mfma_f32_16x16x32_bf16 v[72:75], v[184:187], v[208:211], v[72:75]
	v_mfma_f32_16x16x32_bf16 v[68:71], v[172:175], v[216:219], v[68:71]
	v_mfma_f32_16x16x32_bf16 v[64:67], v[184:187], v[216:219], v[64:67]
	s_setprio 0
	s_barrier
	s_add_i32 s30, s74, s1
	s_mov_b32 m0, s30
	ds_read_b128 v[188:191], v151 offset:16384
	ds_read_b128 v[192:195], v151 offset:17408
	ds_read_b128 v[196:199], v151 offset:18432
	ds_read_b128 v[200:203], v151 offset:19456
	ds_read_b128 v[204:207], v151 offset:20480
	ds_read_b128 v[208:211], v151 offset:21504
	ds_read_b128 v[212:215], v151 offset:22528
	ds_read_b128 v[216:219], v151 offset:23552
	global_load_lds_dwordx4 v130, s[68:69]
	s_add_i32 m0, s30, 0x2000
	s_add_u32 s30, s68, 0x80000
	s_addc_u32 s31, s69, 0
	s_add_i32 s86, s75, s1
	global_load_lds_dwordx4 v134, s[68:69]
	s_mov_b32 m0, s86
	s_nop 0
	global_load_lds_dwordx4 v130, s[30:31]
	s_add_i32 m0, s86, 0x2000
	s_nop 0
	global_load_lds_dwordx4 v134, s[30:31]
	s_mov_b32 m0, s29
	s_nop 0
	global_load_lds_dwordx4 v128, s[70:71]
	s_mov_b32 m0, s33
	s_nop 0
	global_load_lds_dwordx4 v132, s[70:71]
	s_waitcnt vmcnt(8)
	s_waitcnt lgkmcnt(0)
	s_barrier
	s_setprio 1
	s_waitcnt lgkmcnt(0)
	v_mfma_f32_16x16x32_bf16 v[60:63], v[152:155], v[188:191], v[60:63]
	v_mfma_f32_16x16x32_bf16 v[56:59], v[160:163], v[188:191], v[56:59]
	v_mfma_f32_16x16x32_bf16 v[52:55], v[152:155], v[196:199], v[52:55]
	v_mfma_f32_16x16x32_bf16 v[44:47], v[160:163], v[196:199], v[44:47]
	v_mfma_f32_16x16x32_bf16 v[36:39], v[152:155], v[204:207], v[36:39]
	v_mfma_f32_16x16x32_bf16 v[28:31], v[160:163], v[204:207], v[28:31]
	v_mfma_f32_16x16x32_bf16 v[20:23], v[152:155], v[212:215], v[20:23]
	v_mfma_f32_16x16x32_bf16 v[12:15], v[160:163], v[212:215], v[12:15]
	v_mfma_f32_16x16x32_bf16 v[60:63], v[156:159], v[192:195], v[60:63]
	v_mfma_f32_16x16x32_bf16 v[56:59], v[164:167], v[192:195], v[56:59]
	v_mfma_f32_16x16x32_bf16 v[52:55], v[156:159], v[200:203], v[52:55]
	v_mfma_f32_16x16x32_bf16 v[44:47], v[164:167], v[200:203], v[44:47]
	v_mfma_f32_16x16x32_bf16 v[36:39], v[156:159], v[208:211], v[36:39]
	v_mfma_f32_16x16x32_bf16 v[28:31], v[164:167], v[208:211], v[28:31]
	v_mfma_f32_16x16x32_bf16 v[20:23], v[156:159], v[216:219], v[20:23]
	v_mfma_f32_16x16x32_bf16 v[12:15], v[164:167], v[216:219], v[12:15]
	s_setprio 0
	s_setprio 1
	v_mfma_f32_16x16x32_bf16 v[48:51], v[168:171], v[188:191], v[48:51]
	v_mfma_f32_16x16x32_bf16 v[40:43], v[180:183], v[188:191], v[40:43]
	v_mfma_f32_16x16x32_bf16 v[32:35], v[168:171], v[196:199], v[32:35]
	v_mfma_f32_16x16x32_bf16 v[24:27], v[180:183], v[196:199], v[24:27]
	v_mfma_f32_16x16x32_bf16 v[16:19], v[168:171], v[204:207], v[16:19]
	v_mfma_f32_16x16x32_bf16 v[8:11], v[180:183], v[204:207], v[8:11]
	v_mfma_f32_16x16x32_bf16 v[4:7], v[168:171], v[212:215], v[4:7]
	v_mfma_f32_16x16x32_bf16 v[0:3], v[180:183], v[212:215], v[0:3]
	v_mfma_f32_16x16x32_bf16 v[48:51], v[172:175], v[192:195], v[48:51]
	v_mfma_f32_16x16x32_bf16 v[40:43], v[184:187], v[192:195], v[40:43]
	v_mfma_f32_16x16x32_bf16 v[32:35], v[172:175], v[200:203], v[32:35]
	v_mfma_f32_16x16x32_bf16 v[24:27], v[184:187], v[200:203], v[24:27]
	v_mfma_f32_16x16x32_bf16 v[16:19], v[172:175], v[208:211], v[16:19]
	v_mfma_f32_16x16x32_bf16 v[8:11], v[184:187], v[208:211], v[8:11]
	v_mfma_f32_16x16x32_bf16 v[4:7], v[172:175], v[216:219], v[4:7]
	v_mfma_f32_16x16x32_bf16 v[0:3], v[184:187], v[216:219], v[0:3]
	s_setprio 0
	s_barrier
; #define PG8_STAGE(bufoff, gbase, voff) do { _Pragma("unroll") for (int _i = 0; _i < 2; ++_i) \
;         __builtin_amdgcn_global_load_lds((const unsigned*)((const char*)(gbase) + (voff)[_i]), (PG8_LAS unsigned*)(lds + (bufoff) + ldsw + _i * 8192), 16, 0, 0); } while (0)
; #define PG8_LDA(dst, b, h) do { _Pragma("unroll") for (int m = 0; m < 4; ++m) _Pragma("unroll") for (int k = 0; k < 2; ++k) dst[m][k] = *(const PG8_LAS bf16x8*)(lds + PG8_SA(b, h) + aoff + m * 2048 + k * 1024); } while (0)
; #define PG8_LDB(dst, b, h) do { _Pragma("unroll") for (int n = 0; n < 2; ++n) _Pragma("unroll") for (int k = 0; k < 2; ++k) dst[n][k] = *(const PG8_LAS bf16x8*)(lds + PG8_SB(b, h) + boff + n * 2048 + k * 1024); } while (0)
; #define PG8_MMA(ai, bj, At, Bt) do { __builtin_amdgcn_s_setprio(1); _Pragma("unroll") for (int m = 0; m < 4; ++m) _Pragma("unroll") for (int n = 0; n < 2; ++n) _Pragma("unroll") for (int k = 0; k < 2; ++k) \
;         acc[ai][bj][m][n] = __builtin_amdgcn_mfma_f32_16x16x32_bf16(Bt[n][k], At[m][k], acc[ai][bj][m][n], 0, 0, 0); __builtin_amdgcn_s_setprio(0); } while (0)
; #define PG8_WAIT_V(n) asm volatile("s_waitcnt vmcnt(" #n ")" ::: "memory")
; #define PG8_WAIT_L(n) asm volatile("s_waitcnt lgkmcnt(" #n ")" ::: "memory")
; #define PG8_BAR __builtin_amdgcn_s_barrier()
; #define PG8_SCHED __builtin_amdgcn_sched_barrier(0)
; template <class Epi, class Sched, bool ALIGN_EPI = false, bool SP2 = false>
; __device__ __forceinline__ void gemm_phase(PG8_LAS unsigned char* lds, const Gemm g, const Sched& S, const Epi& E) {
;     ...
;             PG8_LDB(B0, 1, 0); PG8_LDB(B1, 1, 1); PG8_SCHED; PG8_LDA(At, 1, 0); PG8_STAGE(PG8_SA(0, 1), a2 + hstep, voffA);
;             PG8_WAIT_V(8); PG8_WAIT_L(0); PG8_BAR; PG8_MMA(0, 0, At, B0); PG8_MMA(0, 1, At, B1); PG8_BAR; PG8_SCHED;
;             PG8_LDA(At, 1, 1); PG8_STAGE(PG8_SB(1, 0), b3, voffB); PG8_STAGE(PG8_SB(1, 1), b3 + hstep, voffB); PG8_STAGE(PG8_SA(1, 0), a3, voffA);
;             PG8_WAIT_V(8); PG8_WAIT_L(0); PG8_BAR; PG8_MMA(1, 0, At, B0); PG8_MMA(1, 1, At, B1); PG8_BAR; PG8_SCHED;
	s_add_i32 s86, 0, 0x18000
	s_add_i32 s87, 0, 0x1c000
	v_add_u32_e32 v164, s86, v147
	v_add_u32_e32 v179, s87, v147
	ds_read_b128 v[152:155], v164
	ds_read_b128 v[156:159], v164 offset:1024
	ds_read_b128 v[160:163], v164 offset:2048
	ds_read_b128 v[164:167], v164 offset:3072
	ds_read_b128 v[168:171], v179
	ds_read_b128 v[172:175], v179 offset:1024
	ds_read_b128 v[180:183], v179 offset:2048
	ds_read_b128 v[184:187], v179 offset:3072
	s_add_u32 s30, s70, 0x80000
	s_addc_u32 s31, s71, 0
	s_mov_b32 m0, s46
	ds_read_b128 v[188:191], v151 offset:32768
	ds_read_b128 v[192:195], v151 offset:33792
	ds_read_b128 v[196:199], v151 offset:34816
	ds_read_b128 v[200:203], v151 offset:35840
	ds_read_b128 v[204:207], v151 offset:36864
	ds_read_b128 v[208:211], v151 offset:37888
	ds_read_b128 v[212:215], v151 offset:38912
	ds_read_b128 v[216:219], v151 offset:39936
	global_load_lds_dwordx4 v128, s[30:31]
	s_mov_b32 m0, s47
	s_nop 0
	global_load_lds_dwordx4 v132, s[30:31]
	s_waitcnt vmcnt(8)
	s_waitcnt lgkmcnt(0)
	s_barrier
	s_setprio 1
	s_waitcnt lgkmcnt(0)
	v_mfma_f32_16x16x32_bf16 v[124:127], v[152:155], v[188:191], v[124:127]
	v_mfma_f32_16x16x32_bf16 v[120:123], v[160:163], v[188:191], v[120:123]
	v_mfma_f32_16x16x32_bf16 v[116:119], v[152:155], v[196:199], v[116:119]
	v_mfma_f32_16x16x32_bf16 v[108:111], v[160:163], v[196:199], v[108:111]
	v_mfma_f32_16x16x32_bf16 v[100:103], v[152:155], v[204:207], v[100:103]
	v_mfma_f32_16x16x32_bf16 v[92:95], v[160:163], v[204:207], v[92:95]
	v_mfma_f32_16x16x32_bf16 v[84:87], v[152:155], v[212:215], v[84:87]
	v_mfma_f32_16x16x32_bf16 v[76:79], v[160:163], v[212:215], v[76:79]
	v_mfma_f32_16x16x32_bf16 v[124:127], v[156:159], v[192:195], v[124:127]
	v_mfma_f32_16x16x32_bf16 v[120:123], v[164:167], v[192:195], v[120:123]
	v_mfma_f32_16x16x32_bf16 v[116:119], v[156:159], v[200:203], v[116:119]
	v_mfma_f32_16x16x32_bf16 v[108:111], v[164:167], v[200:203], v[108:111]
	v_mfma_f32_16x16x32_bf16 v[100:103], v[156:159], v[208:211], v[100:103]
	v_mfma_f32_16x16x32_bf16 v[92:95], v[164:167], v[208:211], v[92:95]
	v_mfma_f32_16x16x32_bf16 v[84:87], v[156:159], v[216:219], v[84:87]
	v_mfma_f32_16x16x32_bf16 v[76:79], v[164:167], v[216:219], v[76:79]
	s_setprio 0
	s_setprio 1
	v_mfma_f32_16x16x32_bf16 v[112:115], v[168:171], v[188:191], v[112:115]
	v_mfma_f32_16x16x32_bf16 v[104:107], v[180:183], v[188:191], v[104:107]
	v_mfma_f32_16x16x32_bf16 v[96:99], v[168:171], v[196:199], v[96:99]
	v_mfma_f32_16x16x32_bf16 v[88:91], v[180:183], v[196:199], v[88:91]
	v_mfma_f32_16x16x32_bf16 v[80:83], v[168:171], v[204:207], v[80:83]
	v_mfma_f32_16x16x32_bf16 v[72:75], v[180:183], v[204:207], v[72:75]
	v_mfma_f32_16x16x32_bf16 v[68:71], v[168:171], v[212:215], v[68:71]
	v_mfma_f32_16x16x32_bf16 v[64:67], v[180:183], v[212:215], v[64:67]
	v_mfma_f32_16x16x32_bf16 v[112:115], v[172:175], v[192:195], v[112:115]
	v_mfma_f32_16x16x32_bf16 v[104:107], v[184:187], v[192:195], v[104:107]
	v_mfma_f32_16x16x32_bf16 v[96:99], v[172:175], v[200:203], v[96:99]
	v_mfma_f32_16x16x32_bf16 v[88:91], v[184:187], v[200:203], v[88:91]
	v_mfma_f32_16x16x32_bf16 v[80:83], v[172:175], v[208:211], v[80:83]
	v_mfma_f32_16x16x32_bf16 v[72:75], v[184:187], v[208:211], v[72:75]
	v_mfma_f32_16x16x32_bf16 v[68:71], v[172:175], v[216:219], v[68:71]
	v_mfma_f32_16x16x32_bf16 v[64:67], v[184:187], v[216:219], v[64:67]
	s_setprio 0
	s_barrier
	s_add_i32 s30, s86, s1
	s_mov_b32 m0, s30
	ds_read_b128 v[188:191], v151 offset:49152
	ds_read_b128 v[192:195], v151 offset:50176
	ds_read_b128 v[196:199], v151 offset:51200
	ds_read_b128 v[200:203], v151 offset:52224
	ds_read_b128 v[204:207], v151 offset:53248
	ds_read_b128 v[208:211], v151 offset:54272
	ds_read_b128 v[212:215], v151 offset:55296
	ds_read_b128 v[216:219], v151 offset:56320
	s_add_u32 s8, s68, 0x80
	s_addc_u32 s9, s69, 0
	global_load_lds_dwordx4 v130, s[8:9]
	s_add_i32 m0, s30, 0x2000
	s_add_u32 s30, s68, 0x80080
	s_addc_u32 s31, s69, 0
	s_add_i32 s68, s87, s1
	global_load_lds_dwordx4 v134, s[8:9]
	s_mov_b32 m0, s68
	s_nop 0
	global_load_lds_dwordx4 v130, s[30:31]
	s_add_i32 m0, s68, 0x2000
	s_nop 0
	global_load_lds_dwordx4 v134, s[30:31]
	s_mov_b32 m0, s72
	s_nop 0
	s_add_u32 s8, s70, 0x80
	s_addc_u32 s9, s71, 0
	global_load_lds_dwordx4 v128, s[8:9]
	s_mov_b32 m0, s73
	s_nop 0
	global_load_lds_dwordx4 v132, s[8:9]
	s_waitcnt vmcnt(8)
	s_waitcnt lgkmcnt(0)
	s_barrier
	s_setprio 1
	s_waitcnt lgkmcnt(0)
	v_mfma_f32_16x16x32_bf16 v[60:63], v[152:155], v[188:191], v[60:63]
	v_mfma_f32_16x16x32_bf16 v[56:59], v[160:163], v[188:191], v[56:59]
	v_mfma_f32_16x16x32_bf16 v[52:55], v[152:155], v[196:199], v[52:55]
	v_mfma_f32_16x16x32_bf16 v[44:47], v[160:163], v[196:199], v[44:47]
	v_mfma_f32_16x16x32_bf16 v[36:39], v[152:155], v[204:207], v[36:39]
	v_mfma_f32_16x16x32_bf16 v[28:31], v[160:163], v[204:207], v[28:31]
	v_mfma_f32_16x16x32_bf16 v[20:23], v[152:155], v[212:215], v[20:23]
	v_mfma_f32_16x16x32_bf16 v[12:15], v[160:163], v[212:215], v[12:15]
	v_mfma_f32_16x16x32_bf16 v[60:63], v[156:159], v[192:195], v[60:63]
	v_mfma_f32_16x16x32_bf16 v[56:59], v[164:167], v[192:195], v[56:59]
	v_mfma_f32_16x16x32_bf16 v[52:55], v[156:159], v[200:203], v[52:55]
	v_mfma_f32_16x16x32_bf16 v[44:47], v[164:167], v[200:203], v[44:47]
	v_mfma_f32_16x16x32_bf16 v[36:39], v[156:159], v[208:211], v[36:39]
	v_mfma_f32_16x16x32_bf16 v[28:31], v[164:167], v[208:211], v[28:31]
	v_mfma_f32_16x16x32_bf16 v[20:23], v[156:159], v[216:219], v[20:23]
	v_mfma_f32_16x16x32_bf16 v[12:15], v[164:167], v[216:219], v[12:15]
	s_setprio 0
	s_setprio 1
	v_mfma_f32_16x16x32_bf16 v[48:51], v[168:171], v[188:191], v[48:51]
	v_mfma_f32_16x16x32_bf16 v[40:43], v[180:183], v[188:191], v[40:43]
	v_mfma_f32_16x16x32_bf16 v[32:35], v[168:171], v[196:199], v[32:35]
	v_mfma_f32_16x16x32_bf16 v[24:27], v[180:183], v[196:199], v[24:27]
	v_mfma_f32_16x16x32_bf16 v[16:19], v[168:171], v[204:207], v[16:19]
	v_mfma_f32_16x16x32_bf16 v[8:11], v[180:183], v[204:207], v[8:11]
	v_mfma_f32_16x16x32_bf16 v[4:7], v[168:171], v[212:215], v[4:7]
	v_mfma_f32_16x16x32_bf16 v[0:3], v[180:183], v[212:215], v[0:3]
	v_mfma_f32_16x16x32_bf16 v[48:51], v[172:175], v[192:195], v[48:51]
	v_mfma_f32_16x16x32_bf16 v[40:43], v[184:187], v[192:195], v[40:43]
	v_mfma_f32_16x16x32_bf16 v[32:35], v[172:175], v[200:203], v[32:35]
	v_mfma_f32_16x16x32_bf16 v[24:27], v[184:187], v[200:203], v[24:27]
	v_mfma_f32_16x16x32_bf16 v[16:19], v[172:175], v[208:211], v[16:19]
	v_mfma_f32_16x16x32_bf16 v[8:11], v[184:187], v[208:211], v[8:11]
	v_mfma_f32_16x16x32_bf16 v[4:7], v[172:175], v[216:219], v[4:7]
	v_mfma_f32_16x16x32_bf16 v[0:3], v[184:187], v[216:219], v[0:3]
	s_setprio 0
	s_barrier
; __device__ __forceinline__ unsigned cvt_pk_bf16(float lo, float hi) { unsigned r; asm volatile("v_cvt_pk_bf16_f32 %0, %1, %2" : "=v"(r) : "v"(lo), "v"(hi)); return r; }
; #define PG8_WAIT_V(n) asm volatile("s_waitcnt vmcnt(" #n ")" ::: "memory")
; #define PG8_BAR __builtin_amdgcn_s_barrier()
;     __device__ __forceinline__ void operator()(const f32x4 (&acc)[2][2][4][2], const Unit& u, int wr, int wc, int fr, int fq) const {
;         const int row0 = u.pm * BM + wr * 64 + fr; const int col0 = u.pn * BM + wc * 32 + 8 * fq;
; #pragma unroll
;         for (int ai = 0; ai < 2; ++ai)
; #pragma unroll
;             for (int m = 0; m < 4; ++m) { bf16_t* rowp = O + (size_t)(row0 + ai * HALF + m * 16) * ldc + col0;
; #pragma unroll
;                 for (int bj = 0; bj < 2; ++bj) { const f32x4 v0 = acc[ai][bj][m][0], v1 = acc[ai][bj][m][1];
;                     u32x4 w; w.x = cvt_pk_bf16(v0[0], v0[1]); w.y = cvt_pk_bf16(v0[2], v0[3]); w.z = cvt_pk_bf16(v1[0], v1[1]); w.w = cvt_pk_bf16(v1[2], v1[3]);
;                     *(u32x4*)(rowp + bj * HALF) = w; } }
; template <class Epi, class Sched, bool ALIGN_EPI = false, bool SP2 = false>
; __device__ __forceinline__ void gemm_phase(PG8_LAS unsigned char* lds, const Gemm g, const Sched& S, const Epi& E) {
;     ...
;         if constexpr (!Epi::AFTER_DRAIN) { E(acc, cur, wr, wc, fr, fq); S.done(cur); }
;         if (!has_next) break;
; #pragma unroll
;         for (int a = 0; a < 2; ++a)
; #pragma unroll
;             for (int b = 0; b < 2; ++b)
; #pragma unroll
;                 for (int m = 0; m < 4; ++m)
; #pragma unroll
;                     for (int n = 0; n < 2; ++n) acc[a][b][m][n] = (f32x4){0.f, 0.f, 0.f, 0.f};
;         cur = nxt; cA = nA; cB = nB; ++ui;
;         if constexpr (ALIGN_EPI) { if (wr == 1) PG8_BAR; }
;     }
;     PG8_WAIT_V(0);
;     if constexpr (!ALIGN_EPI) { if (wr == 0) PG8_BAR; }
	s_add_i32 s85, s85, 2
	s_add_u32 s66, s66, 0x100
	s_addc_u32 s67, s67, 0
	s_add_u32 s83, s83, 0x100
	s_addc_u32 s84, s84, 0
	s_cmp_gt_u32 s85, 29
	s_cbranch_scc0 .LBB0_283
	v_lshl_add_u32 v152, s64, 8, v146
	v_lshl_or_b32 v144, s80, 8, v148
	v_ashrrev_i32_e32 v153, 31, v152
	v_ashrrev_i32_e32 v145, 31, v144
	v_lshlrev_b64 v[154:155], 12, v[152:153]
	v_lshl_add_u64 v[154:155], s[18:19], 0, v[154:155]
	v_lshlrev_b64 v[156:157], 1, v[144:145]
	v_lshl_add_u64 v[144:145], v[154:155], 0, v[156:157]
	v_cvt_pk_bf16_f32 v124, v124, v125
	v_cvt_pk_bf16_f32 v125, v126, v127
	v_cvt_pk_bf16_f32 v126, v120, v121
	v_cvt_pk_bf16_f32 v127, v122, v123
	global_store_dwordx4 v[144:145], v[124:127], off
	v_cvt_pk_bf16_f32 v112, v112, v113
	v_cvt_pk_bf16_f32 v113, v114, v115
	v_cvt_pk_bf16_f32 v114, v104, v105
	v_or_b32_e32 v104, 16, v152
	v_ashrrev_i32_e32 v105, 31, v104
	v_lshlrev_b64 v[104:105], 12, v[104:105]
	v_lshl_add_u64 v[104:105], s[18:19], 0, v[104:105]
	v_cvt_pk_bf16_f32 v115, v106, v107
	global_store_dwordx4 v[144:145], v[112:115], off offset:256
	s_mov_b32 s80, s56
	s_mov_b32 s64, s58
	v_lshl_add_u64 v[112:113], v[104:105], 0, v[156:157]
	v_cvt_pk_bf16_f32 v104, v116, v117
	v_cvt_pk_bf16_f32 v105, v118, v119
	v_cvt_pk_bf16_f32 v106, v108, v109
	v_cvt_pk_bf16_f32 v107, v110, v111
	global_store_dwordx4 v[112:113], v[104:107], off
	v_cvt_pk_bf16_f32 v96, v96, v97
	v_cvt_pk_bf16_f32 v97, v98, v99
	v_cvt_pk_bf16_f32 v98, v88, v89
	v_or_b32_e32 v88, 32, v152
	v_ashrrev_i32_e32 v89, 31, v88
	v_lshlrev_b64 v[88:89], 12, v[88:89]
	v_lshl_add_u64 v[88:89], s[18:19], 0, v[88:89]
	v_cvt_pk_bf16_f32 v99, v90, v91
	global_store_dwordx4 v[112:113], v[96:99], off offset:256
	s_mov_b64 s[68:69], s[62:63]
	s_mov_b64 s[66:67], s[60:61]
	v_lshl_add_u64 v[96:97], v[88:89], 0, v[156:157]
	v_cvt_pk_bf16_f32 v88, v100, v101
	v_cvt_pk_bf16_f32 v89, v102, v103
	v_cvt_pk_bf16_f32 v90, v92, v93
	v_cvt_pk_bf16_f32 v91, v94, v95
	global_store_dwordx4 v[96:97], v[88:91], off
	v_cvt_pk_bf16_f32 v80, v80, v81
	v_cvt_pk_bf16_f32 v81, v82, v83
	v_cvt_pk_bf16_f32 v82, v72, v73
	v_or_b32_e32 v72, 48, v152
	v_ashrrev_i32_e32 v73, 31, v72
	v_lshlrev_b64 v[72:73], 12, v[72:73]
	v_lshl_add_u64 v[72:73], s[18:19], 0, v[72:73]
	v_cvt_pk_bf16_f32 v83, v74, v75
	global_store_dwordx4 v[96:97], v[80:83], off offset:256
	s_nop 1
	v_lshl_add_u64 v[80:81], v[72:73], 0, v[156:157]
	v_cvt_pk_bf16_f32 v72, v84, v85
	v_cvt_pk_bf16_f32 v73, v86, v87
	v_cvt_pk_bf16_f32 v74, v76, v77
	v_cvt_pk_bf16_f32 v75, v78, v79
	global_store_dwordx4 v[80:81], v[72:75], off
	v_cvt_pk_bf16_f32 v68, v68, v69
	v_cvt_pk_bf16_f32 v69, v70, v71
	v_cvt_pk_bf16_f32 v70, v64, v65
	v_cvt_pk_bf16_f32 v71, v66, v67
	global_store_dwordx4 v[80:81], v[68:71], off offset:256
	v_cvt_pk_bf16_f32 v60, v60, v61
	v_cvt_pk_bf16_f32 v61, v62, v63
	v_cvt_pk_bf16_f32 v62, v56, v57
	v_add_co_u32_e32 v56, vcc, s76, v144
	v_lshl_add_u64 v[64:65], v[144:145], 0, s[6:7]
	s_nop 0
	v_addc_co_u32_e32 v57, vcc, 0, v145, vcc
	v_cvt_pk_bf16_f32 v63, v58, v59
	global_store_dwordx4 v[56:57], v[60:63], off
	v_cvt_pk_bf16_f32 v48, v48, v49
	v_cvt_pk_bf16_f32 v49, v50, v51
	v_cvt_pk_bf16_f32 v50, v40, v41
	v_cvt_pk_bf16_f32 v51, v42, v43
	global_store_dwordx4 v[64:65], v[48:51], off offset:256
	v_cvt_pk_bf16_f32 v40, v52, v53
	v_cvt_pk_bf16_f32 v41, v54, v55
	v_cvt_pk_bf16_f32 v42, v44, v45
	v_add_co_u32_e32 v44, vcc, s77, v144
	s_nop 0
	v_lshl_add_u64 v[48:49], v[144:145], 0, s[10:11]
	v_addc_co_u32_e32 v45, vcc, 0, v145, vcc
	v_cvt_pk_bf16_f32 v43, v46, v47
	global_store_dwordx4 v[44:45], v[40:43], off
	v_cvt_pk_bf16_f32 v32, v32, v33
	v_cvt_pk_bf16_f32 v33, v34, v35
	v_cvt_pk_bf16_f32 v34, v24, v25
	v_cvt_pk_bf16_f32 v35, v26, v27
	global_store_dwordx4 v[48:49], v[32:35], off offset:256
	v_cvt_pk_bf16_f32 v24, v36, v37
	v_cvt_pk_bf16_f32 v25, v38, v39
	v_cvt_pk_bf16_f32 v26, v28, v29
	v_add_co_u32_e32 v28, vcc, s78, v144
	s_nop 0
	v_lshl_add_u64 v[32:33], v[144:145], 0, s[36:37]
	v_addc_co_u32_e32 v29, vcc, 0, v145, vcc
	v_cvt_pk_bf16_f32 v27, v30, v31
	global_store_dwordx4 v[28:29], v[24:27], off
	v_cvt_pk_bf16_f32 v16, v16, v17
	v_cvt_pk_bf16_f32 v17, v18, v19
	v_cvt_pk_bf16_f32 v18, v8, v9
	v_cvt_pk_bf16_f32 v19, v10, v11
	global_store_dwordx4 v[32:33], v[16:19], off offset:256
	v_cvt_pk_bf16_f32 v8, v20, v21
	v_cvt_pk_bf16_f32 v9, v22, v23
	v_cvt_pk_bf16_f32 v10, v12, v13
	v_add_co_u32_e32 v12, vcc, s79, v144
	s_nop 0
	v_lshl_add_u64 v[16:17], v[144:145], 0, s[54:55]
	v_addc_co_u32_e32 v13, vcc, 0, v145, vcc
	s_and_b64 vcc, exec, s[4:5]
	v_cvt_pk_bf16_f32 v11, v14, v15
	global_store_dwordx4 v[12:13], v[8:11], off
	v_cvt_pk_bf16_f32 v4, v4, v5
	v_cvt_pk_bf16_f32 v5, v6, v7
	v_cvt_pk_bf16_f32 v6, v0, v1
	v_cvt_pk_bf16_f32 v7, v2, v3
	global_store_dwordx4 v[16:17], v[4:7], off offset:256
	s_cbranch_vccz .LBB0_276
	s_waitcnt vmcnt(0)
	s_cmpk_gt_u32 s0, 0xff
	s_cbranch_scc1 .LBB0_287
	s_barrier

; #define PG8_STAGE(bufoff, gbase, voff) do { _Pragma("unroll") for (int _i = 0; _i < 2; ++_i) \
;         __builtin_amdgcn_global_load_lds((const unsigned*)((const char*)(gbase) + (voff)[_i]), (PG8_LAS unsigned*)(lds + (bufoff) + ldsw + _i * 8192), 16, 0, 0); } while (0)
; #define PG8_LDA(dst, b, h) do { _Pragma("unroll") for (int m = 0; m < 4; ++m) _Pragma("unroll") for (int k = 0; k < 2; ++k) dst[m][k] = *(const PG8_LAS bf16x8*)(lds + PG8_SA(b, h) + aoff + m * 2048 + k * 1024); } while (0)
; #define PG8_LDB(dst, b, h) do { _Pragma("unroll") for (int n = 0; n < 2; ++n) _Pragma("unroll") for (int k = 0; k < 2; ++k) dst[n][k] = *(const PG8_LAS bf16x8*)(lds + PG8_SB(b, h) + boff + n * 2048 + k * 1024); } while (0)
; #define PG8_MMA(ai, bj, At, Bt) do { __builtin_amdgcn_s_setprio(1); _Pragma("unroll") for (int m = 0; m < 4; ++m) _Pragma("unroll") for (int n = 0; n < 2; ++n) _Pragma("unroll") for (int k = 0; k < 2; ++k) \
;         acc[ai][bj][m][n] = __builtin_amdgcn_mfma_f32_16x16x32_bf16(Bt[n][k], At[m][k], acc[ai][bj][m][n], 0, 0, 0); __builtin_amdgcn_s_setprio(0); } while (0)
; #define PG8_WAIT_V(n) asm volatile("s_waitcnt vmcnt(" #n ")" ::: "memory")
; #define PG8_WAIT_L(n) asm volatile("s_waitcnt lgkmcnt(" #n ")" ::: "memory")
; template <class Epi, class Sched, bool ALIGN_EPI = false, bool SP2 = false>
; __device__ __forceinline__ void gemm_phase(PG8_LAS unsigned char* lds, const Gemm g, const Sched& S, const Epi& E) {
;     ...
;             const bool last = (t == nt - 2);
;             const char* a1 = cA + (size_t)(t + 1) * kstep;
;             const char* a2 = last ? nA : cA + (size_t)(t + 2) * kstep; const char* b2 = last ? nB : cB + (size_t)(t + 2) * kstep;
;             const char* a3 = a2 + kstep; const char* b3 = b2 + kstep;
;             if (last && has_next) S.a_ready(nxt);
;             if constexpr (SP2) {
;             PG8_LDB(B0, 0, 0); PG8_LDB(B1, 0, 1); PG8_SCHED; PG8_LDA(At, 0, 0); PG8_STAGE(PG8_SA(1, 1), a1 + hstep, voffA);
;             PG8_WAIT_V(8); PG8_WAIT_L(0); PG8_BAR; PG8_MMA(0, 0, At, B0); PG8_MMA(0, 1, At, B1); PG8_BAR; PG8_SCHED;
;             PG8_LDA(At, 0, 1); PG8_STAGE(PG8_SB(0, 0), b2, voffB); PG8_STAGE(PG8_SB(0, 1), b2 + hstep, voffB); PG8_STAGE(PG8_SA(0, 0), a2, voffA);
;             PG8_WAIT_V(8); PG8_WAIT_L(0); PG8_BAR; PG8_MMA(1, 0, At, B0); PG8_MMA(1, 1, At, B1); PG8_BAR; PG8_SCHED;
.LBB0_404:
	ds_read_b128 v[118:121], v217
	ds_read_b128 v[126:129], v217 offset:1024
	ds_read_b128 v[130:133], v217 offset:2048
	ds_read_b128 v[134:137], v217 offset:3072
	ds_read_b128 v[138:141], v218
	ds_read_b128 v[142:145], v218 offset:1024
	ds_read_b128 v[146:149], v218 offset:2048
	ds_read_b128 v[150:153], v218 offset:3072
	s_add_u32 s30, s10, 0xfff80080
	s_addc_u32 s31, s11, -1
	s_cmp_eq_u32 s65, 28
	s_cselect_b32 s75, s1, s31
	s_cselect_b32 s74, s22, s30
	s_cselect_b32 s73, s33, s63
	s_cselect_b32 s72, s46, s47
	s_add_i32 m0, s77, 0xc000
	ds_read_b128 v[154:157], v219
	ds_read_b128 v[166:169], v219 offset:1024
	ds_read_b128 v[170:173], v219 offset:2048
	ds_read_b128 v[174:177], v219 offset:3072
	ds_read_b128 v[204:207], v219 offset:4096
	ds_read_b128 v[208:211], v219 offset:5120
	ds_read_b128 v[226:229], v219 offset:6144
	ds_read_b128 v[230:233], v219 offset:7168
	global_load_lds_dwordx4 v196, s[10:11]
	s_add_i32 m0, s77, 0xe000
	s_nop 0
	global_load_lds_dwordx4 v198, s[10:11]
	s_waitcnt vmcnt(8)
	s_waitcnt lgkmcnt(0)
	s_barrier
	s_setprio 1
	s_waitcnt lgkmcnt(0)
	v_mfma_f32_16x16x32_bf16 v[162:165], v[118:121], v[154:157], v[162:165]
	v_mfma_f32_16x16x32_bf16 v[60:63], v[130:133], v[154:157], v[60:63]
	v_mfma_f32_16x16x32_bf16 v[122:125], v[118:121], v[170:173], v[122:125]
	v_mfma_f32_16x16x32_bf16 v[52:55], v[130:133], v[170:173], v[52:55]
	v_mfma_f32_16x16x32_bf16 v[108:111], v[118:121], v[204:207], v[108:111]
	v_mfma_f32_16x16x32_bf16 v[44:47], v[130:133], v[204:207], v[44:47]
	v_mfma_f32_16x16x32_bf16 v[104:107], v[118:121], v[226:229], v[104:107]
	v_mfma_f32_16x16x32_bf16 v[40:43], v[130:133], v[226:229], v[40:43]
	v_mfma_f32_16x16x32_bf16 v[162:165], v[126:129], v[166:169], v[162:165]
	v_mfma_f32_16x16x32_bf16 v[60:63], v[134:137], v[166:169], v[60:63]
	v_mfma_f32_16x16x32_bf16 v[122:125], v[126:129], v[174:177], v[122:125]
	v_mfma_f32_16x16x32_bf16 v[52:55], v[134:137], v[174:177], v[52:55]
	v_mfma_f32_16x16x32_bf16 v[108:111], v[126:129], v[208:211], v[108:111]
	v_mfma_f32_16x16x32_bf16 v[44:47], v[134:137], v[208:211], v[44:47]
	v_mfma_f32_16x16x32_bf16 v[104:107], v[126:129], v[230:233], v[104:107]
	v_mfma_f32_16x16x32_bf16 v[40:43], v[134:137], v[230:233], v[40:43]
	s_setprio 0
	s_setprio 1
	v_mfma_f32_16x16x32_bf16 v[158:161], v[138:141], v[154:157], v[158:161]
	v_mfma_f32_16x16x32_bf16 v[56:59], v[146:149], v[154:157], v[56:59]
	v_mfma_f32_16x16x32_bf16 v[112:115], v[138:141], v[170:173], v[114:117]
	v_mfma_f32_16x16x32_bf16 v[48:51], v[146:149], v[170:173], v[48:51]
	v_mfma_f32_16x16x32_bf16 v[100:103], v[138:141], v[204:207], v[100:103]
	v_mfma_f32_16x16x32_bf16 v[36:39], v[146:149], v[204:207], v[36:39]
	v_mfma_f32_16x16x32_bf16 v[96:99], v[138:141], v[226:229], v[96:99]
	v_mfma_f32_16x16x32_bf16 v[32:35], v[146:149], v[226:229], v[32:35]
	v_mfma_f32_16x16x32_bf16 v[158:161], v[142:145], v[166:169], v[158:161]
	v_mfma_f32_16x16x32_bf16 v[56:59], v[150:153], v[166:169], v[56:59]
	v_mfma_f32_16x16x32_bf16 v[112:115], v[142:145], v[174:177], v[112:115]
	v_mfma_f32_16x16x32_bf16 v[48:51], v[150:153], v[174:177], v[48:51]
	v_mfma_f32_16x16x32_bf16 v[100:103], v[142:145], v[208:211], v[100:103]
	v_mfma_f32_16x16x32_bf16 v[36:39], v[150:153], v[208:211], v[36:39]
	v_mfma_f32_16x16x32_bf16 v[96:99], v[142:145], v[230:233], v[96:99]
	v_mfma_f32_16x16x32_bf16 v[32:35], v[150:153], v[230:233], v[32:35]
	s_setprio 0
	s_barrier
	s_add_i32 s30, s85, s29
	s_mov_b32 m0, s30
	ds_read_b128 v[154:157], v219 offset:16384
	ds_read_b128 v[166:169], v219 offset:17408
	ds_read_b128 v[170:173], v219 offset:18432
	ds_read_b128 v[174:177], v219 offset:19456
	ds_read_b128 v[204:207], v219 offset:20480
	ds_read_b128 v[208:211], v219 offset:21504
	ds_read_b128 v[226:229], v219 offset:22528
	ds_read_b128 v[230:233], v219 offset:23552
	global_load_lds_dwordx4 v184, s[72:73]
	s_add_i32 m0, s30, 0x2000
	s_add_u32 s30, s72, 0x80000
	s_addc_u32 s31, s73, 0
	s_add_i32 s71, s86, s29
	global_load_lds_dwordx4 v180, s[72:73]
	s_mov_b32 m0, s71
	s_nop 0
	global_load_lds_dwordx4 v184, s[30:31]
	s_add_i32 m0, s71, 0x2000
	s_nop 0
	global_load_lds_dwordx4 v180, s[30:31]
	s_mov_b32 m0, s77
	s_nop 0
	global_load_lds_dwordx4 v186, s[74:75]
	s_mov_b32 m0, s78
	s_nop 0
	global_load_lds_dwordx4 v182, s[74:75]
	s_waitcnt vmcnt(8)
	s_waitcnt lgkmcnt(0)
	s_barrier
	s_setprio 1
	s_waitcnt lgkmcnt(0)
	v_mfma_f32_16x16x32_bf16 v[92:95], v[118:121], v[154:157], v[92:95]
	v_mfma_f32_16x16x32_bf16 v[28:31], v[130:133], v[154:157], v[28:31]
	v_mfma_f32_16x16x32_bf16 v[84:87], v[118:121], v[170:173], v[84:87]
	v_mfma_f32_16x16x32_bf16 v[20:23], v[130:133], v[170:173], v[20:23]
	v_mfma_f32_16x16x32_bf16 v[76:79], v[118:121], v[204:207], v[76:79]
	v_mfma_f32_16x16x32_bf16 v[12:15], v[130:133], v[204:207], v[12:15]
	v_mfma_f32_16x16x32_bf16 v[72:75], v[118:121], v[226:229], v[72:75]
	v_mfma_f32_16x16x32_bf16 v[8:11], v[130:133], v[226:229], v[8:11]
	v_mfma_f32_16x16x32_bf16 v[92:95], v[126:129], v[166:169], v[92:95]
	v_mfma_f32_16x16x32_bf16 v[28:31], v[134:137], v[166:169], v[28:31]
	v_mfma_f32_16x16x32_bf16 v[84:87], v[126:129], v[174:177], v[84:87]
	v_mfma_f32_16x16x32_bf16 v[20:23], v[134:137], v[174:177], v[20:23]
	v_mfma_f32_16x16x32_bf16 v[76:79], v[126:129], v[208:211], v[76:79]
	v_mfma_f32_16x16x32_bf16 v[12:15], v[134:137], v[208:211], v[12:15]
	v_mfma_f32_16x16x32_bf16 v[72:75], v[126:129], v[230:233], v[72:75]
	v_mfma_f32_16x16x32_bf16 v[8:11], v[134:137], v[230:233], v[8:11]
	s_setprio 0
	s_setprio 1
	v_mfma_f32_16x16x32_bf16 v[88:91], v[138:141], v[154:157], v[88:91]
	v_mfma_f32_16x16x32_bf16 v[24:27], v[146:149], v[154:157], v[24:27]
	v_mfma_f32_16x16x32_bf16 v[80:83], v[138:141], v[170:173], v[80:83]
	v_mfma_f32_16x16x32_bf16 v[16:19], v[146:149], v[170:173], v[16:19]
	v_mfma_f32_16x16x32_bf16 v[68:71], v[138:141], v[204:207], v[68:71]
	v_mfma_f32_16x16x32_bf16 v[4:7], v[146:149], v[204:207], v[4:7]
	v_mfma_f32_16x16x32_bf16 v[64:67], v[138:141], v[226:229], v[64:67]
	v_mfma_f32_16x16x32_bf16 v[0:3], v[146:149], v[226:229], v[0:3]
	v_mfma_f32_16x16x32_bf16 v[88:91], v[142:145], v[166:169], v[88:91]
	v_mfma_f32_16x16x32_bf16 v[24:27], v[150:153], v[166:169], v[24:27]
	v_mfma_f32_16x16x32_bf16 v[80:83], v[142:145], v[174:177], v[80:83]
	v_mfma_f32_16x16x32_bf16 v[16:19], v[150:153], v[174:177], v[16:19]
	v_mfma_f32_16x16x32_bf16 v[68:71], v[142:145], v[208:211], v[68:71]
	v_mfma_f32_16x16x32_bf16 v[4:7], v[150:153], v[208:211], v[4:7]
	v_mfma_f32_16x16x32_bf16 v[64:67], v[142:145], v[230:233], v[64:67]
	v_mfma_f32_16x16x32_bf16 v[0:3], v[150:153], v[230:233], v[0:3]
	s_setprio 0
	s_barrier
; #define PG8_STAGE(bufoff, gbase, voff) do { _Pragma("unroll") for (int _i = 0; _i < 2; ++_i) \
;         __builtin_amdgcn_global_load_lds((const unsigned*)((const char*)(gbase) + (voff)[_i]), (PG8_LAS unsigned*)(lds + (bufoff) + ldsw + _i * 8192), 16, 0, 0); } while (0)
; #define PG8_LDA(dst, b, h) do { _Pragma("unroll") for (int m = 0; m < 4; ++m) _Pragma("unroll") for (int k = 0; k < 2; ++k) dst[m][k] = *(const PG8_LAS bf16x8*)(lds + PG8_SA(b, h) + aoff + m * 2048 + k * 1024); } while (0)
; #define PG8_LDB(dst, b, h) do { _Pragma("unroll") for (int n = 0; n < 2; ++n) _Pragma("unroll") for (int k = 0; k < 2; ++k) dst[n][k] = *(const PG8_LAS bf16x8*)(lds + PG8_SB(b, h) + boff + n * 2048 + k * 1024); } while (0)
; #define PG8_MMA(ai, bj, At, Bt) do { __builtin_amdgcn_s_setprio(1); _Pragma("unroll") for (int m = 0; m < 4; ++m) _Pragma("unroll") for (int n = 0; n < 2; ++n) _Pragma("unroll") for (int k = 0; k < 2; ++k) \
;         acc[ai][bj][m][n] = __builtin_amdgcn_mfma_f32_16x16x32_bf16(Bt[n][k], At[m][k], acc[ai][bj][m][n], 0, 0, 0); __builtin_amdgcn_s_setprio(0); } while (0)
; #define PG8_WAIT_V(n) asm volatile("s_waitcnt vmcnt(" #n ")" ::: "memory")
; #define PG8_WAIT_L(n) asm volatile("s_waitcnt lgkmcnt(" #n ")" ::: "memory")
; #define PG8_BAR __builtin_amdgcn_s_barrier()
; #define PG8_SCHED __builtin_amdgcn_sched_barrier(0)
; template <class Epi, class Sched, bool ALIGN_EPI = false, bool SP2 = false>
; __device__ __forceinline__ void gemm_phase(PG8_LAS unsigned char* lds, const Gemm g, const Sched& S, const Epi& E) {
;     ...
;             PG8_LDB(B0, 1, 0); PG8_LDB(B1, 1, 1); PG8_SCHED; PG8_LDA(At, 1, 0); PG8_STAGE(PG8_SA(0, 1), a2 + hstep, voffA);
;             PG8_WAIT_V(8); PG8_WAIT_L(0); PG8_BAR; PG8_MMA(0, 0, At, B0); PG8_MMA(0, 1, At, B1); PG8_BAR; PG8_SCHED;
;             PG8_LDA(At, 1, 1); PG8_STAGE(PG8_SB(1, 0), b3, voffB); PG8_STAGE(PG8_SB(1, 1), b3 + hstep, voffB); PG8_STAGE(PG8_SA(1, 0), a3, voffA);
;             PG8_WAIT_V(8); PG8_WAIT_L(0); PG8_BAR; PG8_MMA(1, 0, At, B0); PG8_MMA(1, 1, At, B1); PG8_BAR; PG8_SCHED;
;     ...
;         if constexpr (ALIGN_EPI) { if (wr == 0) PG8_BAR; }
	s_add_i32 s71, 0, 0x18000
	v_add_u32_e32 v116, s71, v213
	s_add_i32 s88, 0, 0x1c000
	ds_read_b128 v[118:121], v116
	ds_read_b128 v[126:129], v116 offset:1024
	ds_read_b128 v[130:133], v116 offset:2048
	ds_read_b128 v[134:137], v116 offset:3072
	v_add_u32_e32 v116, s88, v213
	ds_read_b128 v[138:141], v116
	ds_read_b128 v[142:145], v116 offset:1024
	ds_read_b128 v[146:149], v116 offset:2048
	ds_read_b128 v[150:153], v116 offset:3072
	s_add_u32 s30, s74, 0x80000
	s_addc_u32 s31, s75, 0
	s_mov_b32 m0, s79
	ds_read_b128 v[154:157], v219 offset:32768
	ds_read_b128 v[166:169], v219 offset:33792
	ds_read_b128 v[170:173], v219 offset:34816
	ds_read_b128 v[174:177], v219 offset:35840
	ds_read_b128 v[204:207], v219 offset:36864
	ds_read_b128 v[208:211], v219 offset:37888
	ds_read_b128 v[226:229], v219 offset:38912
	ds_read_b128 v[230:233], v219 offset:39936
	global_load_lds_dwordx4 v186, s[30:31]
	s_mov_b32 m0, s80
	s_nop 0
	global_load_lds_dwordx4 v182, s[30:31]
	s_waitcnt vmcnt(8)
	s_waitcnt lgkmcnt(0)
	s_barrier
	s_setprio 1
	s_waitcnt lgkmcnt(0)
	v_mfma_f32_16x16x32_bf16 v[162:165], v[118:121], v[154:157], v[162:165]
	v_mfma_f32_16x16x32_bf16 v[60:63], v[130:133], v[154:157], v[60:63]
	v_mfma_f32_16x16x32_bf16 v[122:125], v[118:121], v[170:173], v[122:125]
	v_mfma_f32_16x16x32_bf16 v[52:55], v[130:133], v[170:173], v[52:55]
	v_mfma_f32_16x16x32_bf16 v[108:111], v[118:121], v[204:207], v[108:111]
	v_mfma_f32_16x16x32_bf16 v[44:47], v[130:133], v[204:207], v[44:47]
	v_mfma_f32_16x16x32_bf16 v[104:107], v[118:121], v[226:229], v[104:107]
	v_mfma_f32_16x16x32_bf16 v[40:43], v[130:133], v[226:229], v[40:43]
	v_mfma_f32_16x16x32_bf16 v[162:165], v[126:129], v[166:169], v[162:165]
	v_mfma_f32_16x16x32_bf16 v[60:63], v[134:137], v[166:169], v[60:63]
	v_mfma_f32_16x16x32_bf16 v[122:125], v[126:129], v[174:177], v[122:125]
	v_mfma_f32_16x16x32_bf16 v[52:55], v[134:137], v[174:177], v[52:55]
	v_mfma_f32_16x16x32_bf16 v[108:111], v[126:129], v[208:211], v[108:111]
	v_mfma_f32_16x16x32_bf16 v[44:47], v[134:137], v[208:211], v[44:47]
	v_mfma_f32_16x16x32_bf16 v[104:107], v[126:129], v[230:233], v[104:107]
	v_mfma_f32_16x16x32_bf16 v[40:43], v[134:137], v[230:233], v[40:43]
	s_setprio 0
	s_setprio 1
	v_mfma_f32_16x16x32_bf16 v[158:161], v[138:141], v[154:157], v[158:161]
	v_mfma_f32_16x16x32_bf16 v[56:59], v[146:149], v[154:157], v[56:59]
	v_mfma_f32_16x16x32_bf16 v[112:115], v[138:141], v[170:173], v[112:115]
	v_mfma_f32_16x16x32_bf16 v[48:51], v[146:149], v[170:173], v[48:51]
	v_mfma_f32_16x16x32_bf16 v[100:103], v[138:141], v[204:207], v[100:103]
	v_mfma_f32_16x16x32_bf16 v[36:39], v[146:149], v[204:207], v[36:39]
	v_mfma_f32_16x16x32_bf16 v[96:99], v[138:141], v[226:229], v[96:99]
	v_mfma_f32_16x16x32_bf16 v[32:35], v[146:149], v[226:229], v[32:35]
	v_mfma_f32_16x16x32_bf16 v[158:161], v[142:145], v[166:169], v[158:161]
	v_mfma_f32_16x16x32_bf16 v[56:59], v[150:153], v[166:169], v[56:59]
	v_mfma_f32_16x16x32_bf16 v[114:117], v[142:145], v[174:177], v[112:115]
	v_mfma_f32_16x16x32_bf16 v[48:51], v[150:153], v[174:177], v[48:51]
	v_mfma_f32_16x16x32_bf16 v[100:103], v[142:145], v[208:211], v[100:103]
	v_mfma_f32_16x16x32_bf16 v[36:39], v[150:153], v[208:211], v[36:39]
	v_mfma_f32_16x16x32_bf16 v[96:99], v[142:145], v[230:233], v[96:99]
	v_mfma_f32_16x16x32_bf16 v[32:35], v[150:153], v[230:233], v[32:35]
	s_setprio 0
	s_barrier
	s_add_i32 s30, s71, s29
	s_mov_b32 m0, s30
	ds_read_b128 v[154:157], v219 offset:49152
	ds_read_b128 v[166:169], v219 offset:50176
	ds_read_b128 v[170:173], v219 offset:51200
	ds_read_b128 v[174:177], v219 offset:52224
	ds_read_b128 v[204:207], v219 offset:53248
	ds_read_b128 v[208:211], v219 offset:54272
	ds_read_b128 v[226:229], v219 offset:55296
	ds_read_b128 v[230:233], v219 offset:56320
	s_add_u32 s52, s72, 0x80
	s_addc_u32 s53, s73, 0
	global_load_lds_dwordx4 v184, s[52:53]
	s_add_i32 m0, s30, 0x2000
	s_add_u32 s30, s72, 0x80080
	s_addc_u32 s31, s73, 0
	s_add_i32 s71, s88, s29
	global_load_lds_dwordx4 v180, s[52:53]
	s_mov_b32 m0, s71
	s_nop 0
	global_load_lds_dwordx4 v184, s[30:31]
	s_add_i32 m0, s71, 0x2000
	s_nop 0
	global_load_lds_dwordx4 v180, s[30:31]
	s_mov_b32 m0, s83
	s_nop 0
	s_add_u32 s52, s74, 0x80
	s_addc_u32 s53, s75, 0
	global_load_lds_dwordx4 v186, s[52:53]
	s_mov_b32 m0, s84
	s_nop 0
	global_load_lds_dwordx4 v182, s[52:53]
	s_waitcnt vmcnt(8)
	s_waitcnt lgkmcnt(0)
	s_barrier
	s_setprio 1
	s_waitcnt lgkmcnt(0)
	v_mfma_f32_16x16x32_bf16 v[92:95], v[118:121], v[154:157], v[92:95]
	v_mfma_f32_16x16x32_bf16 v[28:31], v[130:133], v[154:157], v[28:31]
	v_mfma_f32_16x16x32_bf16 v[84:87], v[118:121], v[170:173], v[84:87]
	v_mfma_f32_16x16x32_bf16 v[20:23], v[130:133], v[170:173], v[20:23]
	v_mfma_f32_16x16x32_bf16 v[76:79], v[118:121], v[204:207], v[76:79]
	v_mfma_f32_16x16x32_bf16 v[12:15], v[130:133], v[204:207], v[12:15]
	v_mfma_f32_16x16x32_bf16 v[72:75], v[118:121], v[226:229], v[72:75]
	v_mfma_f32_16x16x32_bf16 v[8:11], v[130:133], v[226:229], v[8:11]
	v_mfma_f32_16x16x32_bf16 v[92:95], v[126:129], v[166:169], v[92:95]
	v_mfma_f32_16x16x32_bf16 v[28:31], v[134:137], v[166:169], v[28:31]
	v_mfma_f32_16x16x32_bf16 v[84:87], v[126:129], v[174:177], v[84:87]
	v_mfma_f32_16x16x32_bf16 v[20:23], v[134:137], v[174:177], v[20:23]
	v_mfma_f32_16x16x32_bf16 v[76:79], v[126:129], v[208:211], v[76:79]
	v_mfma_f32_16x16x32_bf16 v[12:15], v[134:137], v[208:211], v[12:15]
	v_mfma_f32_16x16x32_bf16 v[72:75], v[126:129], v[230:233], v[72:75]
	v_mfma_f32_16x16x32_bf16 v[8:11], v[134:137], v[230:233], v[8:11]
	s_setprio 0
	s_setprio 1
	v_mfma_f32_16x16x32_bf16 v[88:91], v[138:141], v[154:157], v[88:91]
	v_mfma_f32_16x16x32_bf16 v[24:27], v[146:149], v[154:157], v[24:27]
	v_mfma_f32_16x16x32_bf16 v[80:83], v[138:141], v[170:173], v[80:83]
	v_mfma_f32_16x16x32_bf16 v[16:19], v[146:149], v[170:173], v[16:19]
	v_mfma_f32_16x16x32_bf16 v[68:71], v[138:141], v[204:207], v[68:71]
	v_mfma_f32_16x16x32_bf16 v[4:7], v[146:149], v[204:207], v[4:7]
	v_mfma_f32_16x16x32_bf16 v[64:67], v[138:141], v[226:229], v[64:67]
	v_mfma_f32_16x16x32_bf16 v[0:3], v[146:149], v[226:229], v[0:3]
	v_mfma_f32_16x16x32_bf16 v[88:91], v[142:145], v[166:169], v[88:91]
	v_mfma_f32_16x16x32_bf16 v[24:27], v[150:153], v[166:169], v[24:27]
	v_mfma_f32_16x16x32_bf16 v[80:83], v[142:145], v[174:177], v[80:83]
	v_mfma_f32_16x16x32_bf16 v[16:19], v[150:153], v[174:177], v[16:19]
	v_mfma_f32_16x16x32_bf16 v[68:71], v[142:145], v[208:211], v[68:71]
	v_mfma_f32_16x16x32_bf16 v[4:7], v[150:153], v[208:211], v[4:7]
	v_mfma_f32_16x16x32_bf16 v[64:67], v[142:145], v[230:233], v[64:67]
	v_mfma_f32_16x16x32_bf16 v[0:3], v[150:153], v[230:233], v[0:3]
	s_setprio 0
	s_barrier
	s_add_i32 s65, s65, 2
	s_add_u32 s10, s10, 0x100
	s_addc_u32 s11, s11, 0
	s_add_u32 s47, s47, 0x100
	s_addc_u32 s63, s63, 0
	s_cmp_gt_u32 s65, 29
	s_cbranch_scc0 .LBB0_404
	s_and_b64 vcc, exec, s[54:55]
	s_cbranch_vccz .LBB0_407
	s_barrier

; #define PG8_STAGE(bufoff, gbase, voff) do { _Pragma("unroll") for (int _i = 0; _i < 2; ++_i) \
;         __builtin_amdgcn_global_load_lds((const unsigned*)((const char*)(gbase) + (voff)[_i]), (PG8_LAS unsigned*)(lds + (bufoff) + ldsw + _i * 8192), 16, 0, 0); } while (0)
; #define PG8_LDA(dst, b, h) do { _Pragma("unroll") for (int m = 0; m < 4; ++m) _Pragma("unroll") for (int k = 0; k < 2; ++k) dst[m][k] = *(const PG8_LAS bf16x8*)(lds + PG8_SA(b, h) + aoff + m * 2048 + k * 1024); } while (0)
; #define PG8_LDB(dst, b, h) do { _Pragma("unroll") for (int n = 0; n < 2; ++n) _Pragma("unroll") for (int k = 0; k < 2; ++k) dst[n][k] = *(const PG8_LAS bf16x8*)(lds + PG8_SB(b, h) + boff + n * 2048 + k * 1024); } while (0)
; #define PG8_MMA(ai, bj, At, Bt) do { __builtin_amdgcn_s_setprio(1); _Pragma("unroll") for (int m = 0; m < 4; ++m) _Pragma("unroll") for (int n = 0; n < 2; ++n) _Pragma("unroll") for (int k = 0; k < 2; ++k) \
;         acc[ai][bj][m][n] = __builtin_amdgcn_mfma_f32_16x16x32_bf16(Bt[n][k], At[m][k], acc[ai][bj][m][n], 0, 0, 0); __builtin_amdgcn_s_setprio(0); } while (0)
; #define PG8_WAIT_V(n) asm volatile("s_waitcnt vmcnt(" #n ")" ::: "memory")
; #define PG8_WAIT_L(n) asm volatile("s_waitcnt lgkmcnt(" #n ")" ::: "memory")
; template <class Epi, class Sched, bool ALIGN_EPI = false, bool SP2 = false>
; __device__ __forceinline__ void gemm_phase(PG8_LAS unsigned char* lds, const Gemm g, const Sched& S, const Epi& E) {
;     ...
;             const bool last = (t == nt - 2);
;             const char* a1 = cA + (size_t)(t + 1) * kstep;
;             const char* a2 = last ? nA : cA + (size_t)(t + 2) * kstep; const char* b2 = last ? nB : cB + (size_t)(t + 2) * kstep;
;             const char* a3 = a2 + kstep; const char* b3 = b2 + kstep;
;             if (last && has_next) S.a_ready(nxt);
;             if constexpr (SP2) {
;             PG8_LDB(B0, 0, 0); PG8_LDB(B1, 0, 1); PG8_SCHED; PG8_LDA(At, 0, 0); PG8_STAGE(PG8_SA(1, 1), a1 + hstep, voffA);
;             PG8_WAIT_V(8); PG8_WAIT_L(0); PG8_BAR; PG8_MMA(0, 0, At, B0); PG8_MMA(0, 1, At, B1); PG8_BAR; PG8_SCHED;
;             PG8_LDA(At, 0, 1); PG8_STAGE(PG8_SB(0, 0), b2, voffB); PG8_STAGE(PG8_SB(0, 1), b2 + hstep, voffB); PG8_STAGE(PG8_SA(0, 0), a2, voffA);
;             PG8_WAIT_V(8); PG8_WAIT_L(0); PG8_BAR; PG8_MMA(1, 0, At, B0); PG8_MMA(1, 1, At, B1); PG8_BAR; PG8_SCHED;
.LBB0_552:
	ds_read_b128 v[152:155], v149
	ds_read_b128 v[156:159], v149 offset:1024
	ds_read_b128 v[160:163], v149 offset:2048
	ds_read_b128 v[164:167], v149 offset:3072
	ds_read_b128 v[168:171], v150
	ds_read_b128 v[172:175], v150 offset:1024
	ds_read_b128 v[180:183], v150 offset:2048
	ds_read_b128 v[184:187], v150 offset:3072
	s_add_u32 s34, s26, 0x100
	s_addc_u32 s35, s27, 0
	s_cmpk_eq_i32 s67, 0x54
	s_cselect_b32 s45, s7, s35
	s_cselect_b32 s44, s6, s34
	s_cselect_b32 s37, s9, s66
	s_cselect_b32 s36, s8, s65
	s_add_i32 m0, s29, 0xc000
	ds_read_b128 v[188:191], v151
	ds_read_b128 v[192:195], v151 offset:1024
	ds_read_b128 v[196:199], v151 offset:2048
	ds_read_b128 v[200:203], v151 offset:3072
	ds_read_b128 v[204:207], v151 offset:4096
	ds_read_b128 v[208:211], v151 offset:5120
	ds_read_b128 v[212:215], v151 offset:6144
	ds_read_b128 v[216:219], v151 offset:7168
	global_load_lds_dwordx4 v136, s[26:27]
	s_add_i32 m0, s29, 0xe000
	s_nop 0
	global_load_lds_dwordx4 v138, s[26:27]
	s_waitcnt vmcnt(8)
	s_waitcnt lgkmcnt(0)
	s_barrier
	s_setprio 1
	s_waitcnt lgkmcnt(0)
	v_mfma_f32_16x16x32_bf16 v[124:127], v[152:155], v[188:191], v[124:127]
	v_mfma_f32_16x16x32_bf16 v[120:123], v[160:163], v[188:191], v[120:123]
	v_mfma_f32_16x16x32_bf16 v[116:119], v[152:155], v[196:199], v[116:119]
	v_mfma_f32_16x16x32_bf16 v[108:111], v[160:163], v[196:199], v[108:111]
	v_mfma_f32_16x16x32_bf16 v[100:103], v[152:155], v[204:207], v[100:103]
	v_mfma_f32_16x16x32_bf16 v[92:95], v[160:163], v[204:207], v[92:95]
	v_mfma_f32_16x16x32_bf16 v[84:87], v[152:155], v[212:215], v[84:87]
	v_mfma_f32_16x16x32_bf16 v[76:79], v[160:163], v[212:215], v[76:79]
	v_mfma_f32_16x16x32_bf16 v[124:127], v[156:159], v[192:195], v[124:127]
	v_mfma_f32_16x16x32_bf16 v[120:123], v[164:167], v[192:195], v[120:123]
	v_mfma_f32_16x16x32_bf16 v[116:119], v[156:159], v[200:203], v[116:119]
	v_mfma_f32_16x16x32_bf16 v[108:111], v[164:167], v[200:203], v[108:111]
	v_mfma_f32_16x16x32_bf16 v[100:103], v[156:159], v[208:211], v[100:103]
	v_mfma_f32_16x16x32_bf16 v[92:95], v[164:167], v[208:211], v[92:95]
	v_mfma_f32_16x16x32_bf16 v[84:87], v[156:159], v[216:219], v[84:87]
	v_mfma_f32_16x16x32_bf16 v[76:79], v[164:167], v[216:219], v[76:79]
	s_setprio 0
	s_setprio 1
	v_mfma_f32_16x16x32_bf16 v[112:115], v[168:171], v[188:191], v[112:115]
	v_mfma_f32_16x16x32_bf16 v[104:107], v[180:183], v[188:191], v[104:107]
	v_mfma_f32_16x16x32_bf16 v[96:99], v[168:171], v[196:199], v[96:99]
	v_mfma_f32_16x16x32_bf16 v[88:91], v[180:183], v[196:199], v[88:91]
	v_mfma_f32_16x16x32_bf16 v[80:83], v[168:171], v[204:207], v[80:83]
	v_mfma_f32_16x16x32_bf16 v[72:75], v[180:183], v[204:207], v[72:75]
	v_mfma_f32_16x16x32_bf16 v[68:71], v[168:171], v[212:215], v[68:71]
	v_mfma_f32_16x16x32_bf16 v[64:67], v[180:183], v[212:215], v[64:67]
	v_mfma_f32_16x16x32_bf16 v[112:115], v[172:175], v[192:195], v[112:115]
	v_mfma_f32_16x16x32_bf16 v[104:107], v[184:187], v[192:195], v[104:107]
	v_mfma_f32_16x16x32_bf16 v[96:99], v[172:175], v[200:203], v[96:99]
	v_mfma_f32_16x16x32_bf16 v[88:91], v[184:187], v[200:203], v[88:91]
	v_mfma_f32_16x16x32_bf16 v[80:83], v[172:175], v[208:211], v[80:83]
	v_mfma_f32_16x16x32_bf16 v[72:75], v[184:187], v[208:211], v[72:75]
	v_mfma_f32_16x16x32_bf16 v[68:71], v[172:175], v[216:219], v[68:71]
	v_mfma_f32_16x16x32_bf16 v[64:67], v[184:187], v[216:219], v[64:67]
	s_setprio 0
	s_barrier
	s_add_i32 s26, s55, s1
	s_mov_b32 m0, s26
	ds_read_b128 v[188:191], v151 offset:16384
	ds_read_b128 v[192:195], v151 offset:17408
	ds_read_b128 v[196:199], v151 offset:18432
	ds_read_b128 v[200:203], v151 offset:19456
	ds_read_b128 v[204:207], v151 offset:20480
	ds_read_b128 v[208:211], v151 offset:21504
	ds_read_b128 v[212:215], v151 offset:22528
	ds_read_b128 v[216:219], v151 offset:23552
	global_load_lds_dwordx4 v130, s[36:37]
	s_add_i32 m0, s26, 0x2000
	s_add_u32 s26, s36, 0x160000
	s_addc_u32 s27, s37, 0
	s_add_i32 s30, s56, s1
	global_load_lds_dwordx4 v134, s[36:37]
	s_mov_b32 m0, s30
	s_nop 0
	global_load_lds_dwordx4 v130, s[26:27]
	s_add_i32 m0, s30, 0x2000
	s_nop 0
	global_load_lds_dwordx4 v134, s[26:27]
	s_mov_b32 m0, s29
	s_nop 0
	global_load_lds_dwordx4 v128, s[44:45]
	s_mov_b32 m0, s33
	s_nop 0
	global_load_lds_dwordx4 v132, s[44:45]
	s_waitcnt vmcnt(8)
	s_waitcnt lgkmcnt(0)
	s_barrier
	s_setprio 1
	s_waitcnt lgkmcnt(0)
	v_mfma_f32_16x16x32_bf16 v[60:63], v[152:155], v[188:191], v[60:63]
	v_mfma_f32_16x16x32_bf16 v[56:59], v[160:163], v[188:191], v[56:59]
	v_mfma_f32_16x16x32_bf16 v[52:55], v[152:155], v[196:199], v[52:55]
	v_mfma_f32_16x16x32_bf16 v[44:47], v[160:163], v[196:199], v[44:47]
	v_mfma_f32_16x16x32_bf16 v[36:39], v[152:155], v[204:207], v[36:39]
	v_mfma_f32_16x16x32_bf16 v[28:31], v[160:163], v[204:207], v[28:31]
	v_mfma_f32_16x16x32_bf16 v[20:23], v[152:155], v[212:215], v[20:23]
	v_mfma_f32_16x16x32_bf16 v[12:15], v[160:163], v[212:215], v[12:15]
	v_mfma_f32_16x16x32_bf16 v[60:63], v[156:159], v[192:195], v[60:63]
	v_mfma_f32_16x16x32_bf16 v[56:59], v[164:167], v[192:195], v[56:59]
	v_mfma_f32_16x16x32_bf16 v[52:55], v[156:159], v[200:203], v[52:55]
	v_mfma_f32_16x16x32_bf16 v[44:47], v[164:167], v[200:203], v[44:47]
	v_mfma_f32_16x16x32_bf16 v[36:39], v[156:159], v[208:211], v[36:39]
	v_mfma_f32_16x16x32_bf16 v[28:31], v[164:167], v[208:211], v[28:31]
	v_mfma_f32_16x16x32_bf16 v[20:23], v[156:159], v[216:219], v[20:23]
	v_mfma_f32_16x16x32_bf16 v[12:15], v[164:167], v[216:219], v[12:15]
	s_setprio 0
	s_setprio 1
	v_mfma_f32_16x16x32_bf16 v[48:51], v[168:171], v[188:191], v[48:51]
	v_mfma_f32_16x16x32_bf16 v[40:43], v[180:183], v[188:191], v[40:43]
	v_mfma_f32_16x16x32_bf16 v[32:35], v[168:171], v[196:199], v[32:35]
	v_mfma_f32_16x16x32_bf16 v[24:27], v[180:183], v[196:199], v[24:27]
	v_mfma_f32_16x16x32_bf16 v[16:19], v[168:171], v[204:207], v[16:19]
	v_mfma_f32_16x16x32_bf16 v[8:11], v[180:183], v[204:207], v[8:11]
	v_mfma_f32_16x16x32_bf16 v[4:7], v[168:171], v[212:215], v[4:7]
	v_mfma_f32_16x16x32_bf16 v[0:3], v[180:183], v[212:215], v[0:3]
	v_mfma_f32_16x16x32_bf16 v[48:51], v[172:175], v[192:195], v[48:51]
	v_mfma_f32_16x16x32_bf16 v[40:43], v[184:187], v[192:195], v[40:43]
	v_mfma_f32_16x16x32_bf16 v[32:35], v[172:175], v[200:203], v[32:35]
	v_mfma_f32_16x16x32_bf16 v[24:27], v[184:187], v[200:203], v[24:27]
	v_mfma_f32_16x16x32_bf16 v[16:19], v[172:175], v[208:211], v[16:19]
	v_mfma_f32_16x16x32_bf16 v[8:11], v[184:187], v[208:211], v[8:11]
	v_mfma_f32_16x16x32_bf16 v[4:7], v[172:175], v[216:219], v[4:7]
	v_mfma_f32_16x16x32_bf16 v[0:3], v[184:187], v[216:219], v[0:3]
	s_setprio 0
	s_barrier
; #define PG8_STAGE(bufoff, gbase, voff) do { _Pragma("unroll") for (int _i = 0; _i < 2; ++_i) \
;         __builtin_amdgcn_global_load_lds((const unsigned*)((const char*)(gbase) + (voff)[_i]), (PG8_LAS unsigned*)(lds + (bufoff) + ldsw + _i * 8192), 16, 0, 0); } while (0)
; #define PG8_LDA(dst, b, h) do { _Pragma("unroll") for (int m = 0; m < 4; ++m) _Pragma("unroll") for (int k = 0; k < 2; ++k) dst[m][k] = *(const PG8_LAS bf16x8*)(lds + PG8_SA(b, h) + aoff + m * 2048 + k * 1024); } while (0)
; #define PG8_LDB(dst, b, h) do { _Pragma("unroll") for (int n = 0; n < 2; ++n) _Pragma("unroll") for (int k = 0; k < 2; ++k) dst[n][k] = *(const PG8_LAS bf16x8*)(lds + PG8_SB(b, h) + boff + n * 2048 + k * 1024); } while (0)
; #define PG8_MMA(ai, bj, At, Bt) do { __builtin_amdgcn_s_setprio(1); _Pragma("unroll") for (int m = 0; m < 4; ++m) _Pragma("unroll") for (int n = 0; n < 2; ++n) _Pragma("unroll") for (int k = 0; k < 2; ++k) \
;         acc[ai][bj][m][n] = __builtin_amdgcn_mfma_f32_16x16x32_bf16(Bt[n][k], At[m][k], acc[ai][bj][m][n], 0, 0, 0); __builtin_amdgcn_s_setprio(0); } while (0)
; #define PG8_WAIT_V(n) asm volatile("s_waitcnt vmcnt(" #n ")" ::: "memory")
; #define PG8_WAIT_L(n) asm volatile("s_waitcnt lgkmcnt(" #n ")" ::: "memory")
; #define PG8_BAR __builtin_amdgcn_s_barrier()
; #define PG8_SCHED __builtin_amdgcn_sched_barrier(0)
; template <class Epi, class Sched, bool ALIGN_EPI = false, bool SP2 = false>
; __device__ __forceinline__ void gemm_phase(PG8_LAS unsigned char* lds, const Gemm g, const Sched& S, const Epi& E) {
;     ...
;             PG8_LDB(B0, 1, 0); PG8_LDB(B1, 1, 1); PG8_SCHED; PG8_LDA(At, 1, 0); PG8_STAGE(PG8_SA(0, 1), a2 + hstep, voffA);
;             PG8_WAIT_V(8); PG8_WAIT_L(0); PG8_BAR; PG8_MMA(0, 0, At, B0); PG8_MMA(0, 1, At, B1); PG8_BAR; PG8_SCHED;
;             PG8_LDA(At, 1, 1); PG8_STAGE(PG8_SB(1, 0), b3, voffB); PG8_STAGE(PG8_SB(1, 1), b3 + hstep, voffB); PG8_STAGE(PG8_SA(1, 0), a3, voffA);
;             PG8_WAIT_V(8); PG8_WAIT_L(0); PG8_BAR; PG8_MMA(1, 0, At, B0); PG8_MMA(1, 1, At, B1); PG8_BAR; PG8_SCHED;
	s_add_i32 s30, 0, 0x18000
	s_add_i32 s31, 0, 0x1c000
	v_add_u32_e32 v164, s30, v147
	v_add_u32_e32 v184, s31, v147
	ds_read_b128 v[152:155], v164
	ds_read_b128 v[156:159], v164 offset:1024
	ds_read_b128 v[160:163], v164 offset:2048
	ds_read_b128 v[164:167], v164 offset:3072
	ds_read_b128 v[168:171], v184
	ds_read_b128 v[172:175], v184 offset:1024
	ds_read_b128 v[180:183], v184 offset:2048
	ds_read_b128 v[184:187], v184 offset:3072
	s_add_u32 s26, s44, 0x160000
	s_addc_u32 s27, s45, 0
	s_mov_b32 m0, s46
	ds_read_b128 v[188:191], v151 offset:32768
	ds_read_b128 v[192:195], v151 offset:33792
	ds_read_b128 v[196:199], v151 offset:34816
	ds_read_b128 v[200:203], v151 offset:35840
	ds_read_b128 v[204:207], v151 offset:36864
	ds_read_b128 v[208:211], v151 offset:37888
	ds_read_b128 v[212:215], v151 offset:38912
	ds_read_b128 v[216:219], v151 offset:39936
	global_load_lds_dwordx4 v128, s[26:27]
	s_mov_b32 m0, s47
	s_nop 0
	global_load_lds_dwordx4 v132, s[26:27]
	s_waitcnt vmcnt(8)
	s_waitcnt lgkmcnt(0)
	s_barrier
	s_setprio 1
	s_waitcnt lgkmcnt(0)
	v_mfma_f32_16x16x32_bf16 v[124:127], v[152:155], v[188:191], v[124:127]
	v_mfma_f32_16x16x32_bf16 v[120:123], v[160:163], v[188:191], v[120:123]
	v_mfma_f32_16x16x32_bf16 v[116:119], v[152:155], v[196:199], v[116:119]
	v_mfma_f32_16x16x32_bf16 v[108:111], v[160:163], v[196:199], v[108:111]
	v_mfma_f32_16x16x32_bf16 v[100:103], v[152:155], v[204:207], v[100:103]
	v_mfma_f32_16x16x32_bf16 v[92:95], v[160:163], v[204:207], v[92:95]
	v_mfma_f32_16x16x32_bf16 v[84:87], v[152:155], v[212:215], v[84:87]
	v_mfma_f32_16x16x32_bf16 v[76:79], v[160:163], v[212:215], v[76:79]
	v_mfma_f32_16x16x32_bf16 v[124:127], v[156:159], v[192:195], v[124:127]
	v_mfma_f32_16x16x32_bf16 v[120:123], v[164:167], v[192:195], v[120:123]
	v_mfma_f32_16x16x32_bf16 v[116:119], v[156:159], v[200:203], v[116:119]
	v_mfma_f32_16x16x32_bf16 v[108:111], v[164:167], v[200:203], v[108:111]
	v_mfma_f32_16x16x32_bf16 v[100:103], v[156:159], v[208:211], v[100:103]
	v_mfma_f32_16x16x32_bf16 v[92:95], v[164:167], v[208:211], v[92:95]
	v_mfma_f32_16x16x32_bf16 v[84:87], v[156:159], v[216:219], v[84:87]
	v_mfma_f32_16x16x32_bf16 v[76:79], v[164:167], v[216:219], v[76:79]
	s_setprio 0
	s_setprio 1
	v_mfma_f32_16x16x32_bf16 v[112:115], v[168:171], v[188:191], v[112:115]
	v_mfma_f32_16x16x32_bf16 v[104:107], v[180:183], v[188:191], v[104:107]
	v_mfma_f32_16x16x32_bf16 v[96:99], v[168:171], v[196:199], v[96:99]
	v_mfma_f32_16x16x32_bf16 v[88:91], v[180:183], v[196:199], v[88:91]
	v_mfma_f32_16x16x32_bf16 v[80:83], v[168:171], v[204:207], v[80:83]
	v_mfma_f32_16x16x32_bf16 v[72:75], v[180:183], v[204:207], v[72:75]
	v_mfma_f32_16x16x32_bf16 v[68:71], v[168:171], v[212:215], v[68:71]
	v_mfma_f32_16x16x32_bf16 v[64:67], v[180:183], v[212:215], v[64:67]
	v_mfma_f32_16x16x32_bf16 v[112:115], v[172:175], v[192:195], v[112:115]
	v_mfma_f32_16x16x32_bf16 v[104:107], v[184:187], v[192:195], v[104:107]
	v_mfma_f32_16x16x32_bf16 v[96:99], v[172:175], v[200:203], v[96:99]
	v_mfma_f32_16x16x32_bf16 v[88:91], v[184:187], v[200:203], v[88:91]
	v_mfma_f32_16x16x32_bf16 v[80:83], v[172:175], v[208:211], v[80:83]
	v_mfma_f32_16x16x32_bf16 v[72:75], v[184:187], v[208:211], v[72:75]
	v_mfma_f32_16x16x32_bf16 v[68:71], v[172:175], v[216:219], v[68:71]
	v_mfma_f32_16x16x32_bf16 v[64:67], v[184:187], v[216:219], v[64:67]
	s_setprio 0
	s_barrier
	s_add_i32 s26, s30, s1
	s_mov_b32 m0, s26
	ds_read_b128 v[188:191], v151 offset:49152
	ds_read_b128 v[192:195], v151 offset:50176
	ds_read_b128 v[196:199], v151 offset:51200
	ds_read_b128 v[200:203], v151 offset:52224
	ds_read_b128 v[204:207], v151 offset:53248
	ds_read_b128 v[208:211], v151 offset:54272
	ds_read_b128 v[212:215], v151 offset:55296
	ds_read_b128 v[216:219], v151 offset:56320
	s_add_u32 s10, s36, 0x80
	s_addc_u32 s11, s37, 0
	global_load_lds_dwordx4 v130, s[10:11]
	s_add_i32 m0, s26, 0x2000
	s_add_u32 s26, s36, 0x160080
	s_addc_u32 s27, s37, 0
	s_add_i32 s30, s31, s1
	global_load_lds_dwordx4 v134, s[10:11]
	s_mov_b32 m0, s30
	s_nop 0
	global_load_lds_dwordx4 v130, s[26:27]
	s_add_i32 m0, s30, 0x2000
	s_nop 0
	global_load_lds_dwordx4 v134, s[26:27]
	s_mov_b32 m0, s53
	s_nop 0
	s_add_u32 s10, s44, 0x80
	s_addc_u32 s11, s45, 0
	global_load_lds_dwordx4 v128, s[10:11]
	s_mov_b32 m0, s54
	s_nop 0
	global_load_lds_dwordx4 v132, s[10:11]
	s_waitcnt vmcnt(8)
	s_waitcnt lgkmcnt(0)
	s_barrier
	s_setprio 1
	s_waitcnt lgkmcnt(0)
	v_mfma_f32_16x16x32_bf16 v[60:63], v[152:155], v[188:191], v[60:63]
	v_mfma_f32_16x16x32_bf16 v[56:59], v[160:163], v[188:191], v[56:59]
	v_mfma_f32_16x16x32_bf16 v[52:55], v[152:155], v[196:199], v[52:55]
	v_mfma_f32_16x16x32_bf16 v[44:47], v[160:163], v[196:199], v[44:47]
	v_mfma_f32_16x16x32_bf16 v[36:39], v[152:155], v[204:207], v[36:39]
	v_mfma_f32_16x16x32_bf16 v[28:31], v[160:163], v[204:207], v[28:31]
	v_mfma_f32_16x16x32_bf16 v[20:23], v[152:155], v[212:215], v[20:23]
	v_mfma_f32_16x16x32_bf16 v[12:15], v[160:163], v[212:215], v[12:15]
	v_mfma_f32_16x16x32_bf16 v[60:63], v[156:159], v[192:195], v[60:63]
	v_mfma_f32_16x16x32_bf16 v[56:59], v[164:167], v[192:195], v[56:59]
	v_mfma_f32_16x16x32_bf16 v[52:55], v[156:159], v[200:203], v[52:55]
	v_mfma_f32_16x16x32_bf16 v[44:47], v[164:167], v[200:203], v[44:47]
	v_mfma_f32_16x16x32_bf16 v[36:39], v[156:159], v[208:211], v[36:39]
	v_mfma_f32_16x16x32_bf16 v[28:31], v[164:167], v[208:211], v[28:31]
	v_mfma_f32_16x16x32_bf16 v[20:23], v[156:159], v[216:219], v[20:23]
	v_mfma_f32_16x16x32_bf16 v[12:15], v[164:167], v[216:219], v[12:15]
	s_setprio 0
	s_setprio 1
	v_mfma_f32_16x16x32_bf16 v[48:51], v[168:171], v[188:191], v[48:51]
	v_mfma_f32_16x16x32_bf16 v[40:43], v[180:183], v[188:191], v[40:43]
	v_mfma_f32_16x16x32_bf16 v[32:35], v[168:171], v[196:199], v[32:35]
	v_mfma_f32_16x16x32_bf16 v[24:27], v[180:183], v[196:199], v[24:27]
	v_mfma_f32_16x16x32_bf16 v[16:19], v[168:171], v[204:207], v[16:19]
	v_mfma_f32_16x16x32_bf16 v[8:11], v[180:183], v[204:207], v[8:11]
	v_mfma_f32_16x16x32_bf16 v[4:7], v[168:171], v[212:215], v[4:7]
	v_mfma_f32_16x16x32_bf16 v[0:3], v[180:183], v[212:215], v[0:3]
	v_mfma_f32_16x16x32_bf16 v[48:51], v[172:175], v[192:195], v[48:51]
	v_mfma_f32_16x16x32_bf16 v[40:43], v[184:187], v[192:195], v[40:43]
	v_mfma_f32_16x16x32_bf16 v[32:35], v[172:175], v[200:203], v[32:35]
	v_mfma_f32_16x16x32_bf16 v[24:27], v[184:187], v[200:203], v[24:27]
	v_mfma_f32_16x16x32_bf16 v[16:19], v[172:175], v[208:211], v[16:19]
	v_mfma_f32_16x16x32_bf16 v[8:11], v[184:187], v[208:211], v[8:11]
	v_mfma_f32_16x16x32_bf16 v[4:7], v[172:175], v[216:219], v[4:7]
	v_mfma_f32_16x16x32_bf16 v[0:3], v[184:187], v[216:219], v[0:3]
	s_setprio 0
	s_barrier
; __device__ __forceinline__ unsigned cvt_pk_bf16(float lo, float hi) { unsigned r; asm volatile("v_cvt_pk_bf16_f32 %0, %1, %2" : "=v"(r) : "v"(lo), "v"(hi)); return r; }
; #define PG8_WAIT_V(n) asm volatile("s_waitcnt vmcnt(" #n ")" ::: "memory")
; #define PG8_BAR __builtin_amdgcn_s_barrier()
;     __device__ __forceinline__ void operator()(const f32x4 (&acc)[2][2][4][2], const Unit& u, int wr, int wc, int fr, int fq) const {
;         const int row0 = u.pm * BM + wr * 64 + fr; const int col0 = u.pn * BM + wc * 32 + 8 * fq;
; #pragma unroll
;         for (int ai = 0; ai < 2; ++ai)
; #pragma unroll
;             for (int m = 0; m < 4; ++m) { bf16_t* rowp = O + (size_t)(row0 + ai * HALF + m * 16) * ldc + col0;
; #pragma unroll
;                 for (int bj = 0; bj < 2; ++bj) { const f32x4 v0 = acc[ai][bj][m][0], v1 = acc[ai][bj][m][1];
;                     u32x4 w; w.x = cvt_pk_bf16(v0[0], v0[1]); w.y = cvt_pk_bf16(v0[2], v0[3]); w.z = cvt_pk_bf16(v1[0], v1[1]); w.w = cvt_pk_bf16(v1[2], v1[3]);
;                     *(u32x4*)(rowp + bj * HALF) = w; } }
; template <class Epi, class Sched, bool ALIGN_EPI = false, bool SP2 = false>
; __device__ __forceinline__ void gemm_phase(PG8_LAS unsigned char* lds, const Gemm g, const Sched& S, const Epi& E) {
;     ...
;         if constexpr (!Epi::AFTER_DRAIN) { E(acc, cur, wr, wc, fr, fq); S.done(cur); }
;         if (!has_next) break;
; #pragma unroll
;         for (int a = 0; a < 2; ++a)
; #pragma unroll
;             for (int b = 0; b < 2; ++b)
; #pragma unroll
;                 for (int m = 0; m < 4; ++m)
; #pragma unroll
;                     for (int n = 0; n < 2; ++n) acc[a][b][m][n] = (f32x4){0.f, 0.f, 0.f, 0.f};
;         cur = nxt; cA = nA; cB = nB; ++ui;
;         if constexpr (ALIGN_EPI) { if (wr == 1) PG8_BAR; }
;     }
;     PG8_WAIT_V(0);
;     if constexpr (!ALIGN_EPI) { if (wr == 0) PG8_BAR; }
	s_add_i32 s67, s67, 2
	s_add_u32 s65, s65, 0x100
	s_addc_u32 s66, s66, 0
	s_cmpk_gt_u32 s67, 0x55
	s_mov_b64 s[26:27], s[34:35]
	s_cbranch_scc0 .LBB0_552
	v_lshl_add_u32 v152, s63, 8, v146
	v_lshl_or_b32 v144, s64, 8, v148
	v_ashrrev_i32_e32 v153, 31, v152
	v_ashrrev_i32_e32 v145, 31, v144
	v_lshlrev_b64 v[154:155], 12, v[152:153]
	v_lshl_add_u64 v[154:155], s[18:19], 0, v[154:155]
	v_lshlrev_b64 v[156:157], 1, v[144:145]
	v_lshl_add_u64 v[144:145], v[154:155], 0, v[156:157]
	v_cvt_pk_bf16_f32 v124, v124, v125
	v_cvt_pk_bf16_f32 v125, v126, v127
	v_cvt_pk_bf16_f32 v126, v120, v121
	v_cvt_pk_bf16_f32 v127, v122, v123
	global_store_dwordx4 v[144:145], v[124:127], off
	v_cvt_pk_bf16_f32 v112, v112, v113
	v_cvt_pk_bf16_f32 v113, v114, v115
	v_cvt_pk_bf16_f32 v114, v104, v105
	v_or_b32_e32 v104, 16, v152
	v_ashrrev_i32_e32 v105, 31, v104
	v_lshlrev_b64 v[104:105], 12, v[104:105]
	v_lshl_add_u64 v[104:105], s[18:19], 0, v[104:105]
	v_cvt_pk_bf16_f32 v115, v106, v107
	global_store_dwordx4 v[144:145], v[112:115], off offset:256
	s_mov_b32 s64, s61
	s_mov_b32 s63, s62
	v_lshl_add_u64 v[112:113], v[104:105], 0, v[156:157]
	v_cvt_pk_bf16_f32 v104, v116, v117
	v_cvt_pk_bf16_f32 v105, v118, v119
	v_cvt_pk_bf16_f32 v106, v108, v109
	v_cvt_pk_bf16_f32 v107, v110, v111
	global_store_dwordx4 v[112:113], v[104:107], off
	v_cvt_pk_bf16_f32 v96, v96, v97
	v_cvt_pk_bf16_f32 v97, v98, v99
	v_cvt_pk_bf16_f32 v98, v88, v89
	v_or_b32_e32 v88, 32, v152
	v_ashrrev_i32_e32 v89, 31, v88
	v_lshlrev_b64 v[88:89], 12, v[88:89]
	v_lshl_add_u64 v[88:89], s[18:19], 0, v[88:89]
	v_cvt_pk_bf16_f32 v99, v90, v91
	global_store_dwordx4 v[112:113], v[96:99], off offset:256
	s_mov_b64 s[34:35], s[8:9]
	s_mov_b64 s[26:27], s[6:7]
	v_lshl_add_u64 v[96:97], v[88:89], 0, v[156:157]
	v_cvt_pk_bf16_f32 v88, v100, v101
	v_cvt_pk_bf16_f32 v89, v102, v103
	v_cvt_pk_bf16_f32 v90, v92, v93
	v_cvt_pk_bf16_f32 v91, v94, v95
	global_store_dwordx4 v[96:97], v[88:91], off
	v_cvt_pk_bf16_f32 v80, v80, v81
	v_cvt_pk_bf16_f32 v81, v82, v83
	v_cvt_pk_bf16_f32 v82, v72, v73
	v_or_b32_e32 v72, 48, v152
	v_ashrrev_i32_e32 v73, 31, v72
	v_lshlrev_b64 v[72:73], 12, v[72:73]
	v_lshl_add_u64 v[72:73], s[18:19], 0, v[72:73]
	v_cvt_pk_bf16_f32 v83, v74, v75
	global_store_dwordx4 v[96:97], v[80:83], off offset:256
	s_nop 1
	v_lshl_add_u64 v[80:81], v[72:73], 0, v[156:157]
	v_cvt_pk_bf16_f32 v72, v84, v85
	v_cvt_pk_bf16_f32 v73, v86, v87
	v_cvt_pk_bf16_f32 v74, v76, v77
	v_cvt_pk_bf16_f32 v75, v78, v79
	global_store_dwordx4 v[80:81], v[72:75], off
	v_cvt_pk_bf16_f32 v68, v68, v69
	v_cvt_pk_bf16_f32 v69, v70, v71
	v_cvt_pk_bf16_f32 v70, v64, v65
	v_cvt_pk_bf16_f32 v71, v66, v67
	global_store_dwordx4 v[80:81], v[68:71], off offset:256
	v_cvt_pk_bf16_f32 v60, v60, v61
	v_cvt_pk_bf16_f32 v61, v62, v63
	v_cvt_pk_bf16_f32 v62, v56, v57
	v_add_co_u32_e32 v56, vcc, s57, v144
	v_lshl_add_u64 v[64:65], v[144:145], 0, s[16:17]
	s_nop 0
	v_addc_co_u32_e32 v57, vcc, 0, v145, vcc
	v_cvt_pk_bf16_f32 v63, v58, v59
	global_store_dwordx4 v[56:57], v[60:63], off
	v_cvt_pk_bf16_f32 v48, v48, v49
	v_cvt_pk_bf16_f32 v49, v50, v51
	v_cvt_pk_bf16_f32 v50, v40, v41
	v_cvt_pk_bf16_f32 v51, v42, v43
	global_store_dwordx4 v[64:65], v[48:51], off offset:256
	v_cvt_pk_bf16_f32 v40, v52, v53
	v_cvt_pk_bf16_f32 v41, v54, v55
	v_cvt_pk_bf16_f32 v42, v44, v45
	v_add_co_u32_e32 v44, vcc, s58, v144
	s_nop 0
	v_lshl_add_u64 v[48:49], v[144:145], 0, s[20:21]
	v_addc_co_u32_e32 v45, vcc, 0, v145, vcc
	v_cvt_pk_bf16_f32 v43, v46, v47
	global_store_dwordx4 v[44:45], v[40:43], off
	v_cvt_pk_bf16_f32 v32, v32, v33
	v_cvt_pk_bf16_f32 v33, v34, v35
	v_cvt_pk_bf16_f32 v34, v24, v25
	v_cvt_pk_bf16_f32 v35, v26, v27
	global_store_dwordx4 v[48:49], v[32:35], off offset:256
	v_cvt_pk_bf16_f32 v24, v36, v37
	v_cvt_pk_bf16_f32 v25, v38, v39
	v_cvt_pk_bf16_f32 v26, v28, v29
	v_add_co_u32_e32 v28, vcc, s59, v144
	s_nop 0
	v_lshl_add_u64 v[32:33], v[144:145], 0, s[22:23]
	v_addc_co_u32_e32 v29, vcc, 0, v145, vcc
	v_cvt_pk_bf16_f32 v27, v30, v31
	global_store_dwordx4 v[28:29], v[24:27], off
	v_cvt_pk_bf16_f32 v16, v16, v17
	v_cvt_pk_bf16_f32 v17, v18, v19
	v_cvt_pk_bf16_f32 v18, v8, v9
	v_cvt_pk_bf16_f32 v19, v10, v11
	global_store_dwordx4 v[32:33], v[16:19], off offset:256
	v_cvt_pk_bf16_f32 v8, v20, v21
	v_cvt_pk_bf16_f32 v9, v22, v23
	v_cvt_pk_bf16_f32 v10, v12, v13
	v_add_co_u32_e32 v12, vcc, s60, v144
	s_nop 0
	v_lshl_add_u64 v[16:17], v[144:145], 0, s[24:25]
	v_addc_co_u32_e32 v13, vcc, 0, v145, vcc
	s_and_b64 vcc, exec, s[4:5]
	v_cvt_pk_bf16_f32 v11, v14, v15
	global_store_dwordx4 v[12:13], v[8:11], off
	v_cvt_pk_bf16_f32 v4, v4, v5
	v_cvt_pk_bf16_f32 v5, v6, v7
	v_cvt_pk_bf16_f32 v6, v0, v1
	v_cvt_pk_bf16_f32 v7, v2, v3
	global_store_dwordx4 v[16:17], v[4:7], off offset:256
	s_cbranch_vccz .LBB0_541
	s_waitcnt vmcnt(0)
	s_cmpk_gt_u32 s0, 0xff
	s_cbranch_scc1 .LBB0_556
	s_barrier
